# V half time-sliced too: per-slice axpy with transposing cross-lane reduction, x updated slice by slice, compiled epilogue reused for the fused adaLN
# speedup vs baseline: 1.0698x; 1.0376x over previous
;     ...
;     for (int t = 0; t < NTL; ++t) { b0[t] = *(const u32x4_t*)(up[t]); b1[t] = *(const u32x4_t*)(up[t] + 64); }
;     ...
;     for (int m = 0; m < 16; m += 2) {
;         const u32x4_t a0 = *(const u32x4_t*)(hp + m * 64), a1 = *(const u32x4_t*)(hp + m * 64 + 64);
; #pragma unroll
;         for (int t = 0; t < NTL; ++t) FP8MM(a0, b0[t], acc[t]);
;         if (m + 2 < 16) {
; #pragma unroll
;             for (int t = 0; t < NTL; ++t) b0[t] = *(const u32x4_t*)(up[t] + (m + 2) * 64);
;         }
; #pragma unroll
;         for (int t = 0; t < NTL; ++t) FP8MM(a1, b1[t], acc[t]);
;         if (m + 3 < 16) {
; #pragma unroll
;             for (int t = 0; t < NTL; ++t) b1[t] = *(const u32x4_t*)(up[t] + (m + 3) * 64);
;         }
;     }
.Lg1_loop:
	s_waitcnt vmcnt(16)
	v_cvt_pk_f32_fp8_e32 v[10:11], v180
	v_cvt_pk_f32_fp8_sdwa v[12:13], v180 src0_sel:WORD_1
	v_cvt_pk_f32_fp8_e32 v[14:15], v181
	v_cvt_pk_f32_fp8_sdwa v[16:17], v181 src0_sel:WORD_1
	v_cvt_pk_f32_fp8_e32 v[18:19], v182
	v_cvt_pk_f32_fp8_sdwa v[20:21], v182 src0_sel:WORD_1
	v_cvt_pk_f32_fp8_e32 v[22:23], v183
	v_cvt_pk_f32_fp8_sdwa v[24:25], v183 src0_sel:WORD_1
	v_cvt_pk_f32_fp8_e32 v[26:27], v184
	v_cvt_pk_f32_fp8_sdwa v[28:29], v184 src0_sel:WORD_1
	v_cvt_pk_f32_fp8_e32 v[30:31], v185
	v_cvt_pk_f32_fp8_sdwa v[32:33], v185 src0_sel:WORD_1
	v_cvt_pk_f32_fp8_e32 v[34:35], v186
	v_cvt_pk_f32_fp8_sdwa v[36:37], v186 src0_sel:WORD_1
	v_cvt_pk_f32_fp8_e32 v[38:39], v187
	v_cvt_pk_f32_fp8_sdwa v[40:41], v187 src0_sel:WORD_1
	v_pk_fma_f32 v[10:11], v[26:27], v[8:9], v[10:11]
	v_pk_fma_f32 v[12:13], v[28:29], v[8:9], v[12:13]
	v_pk_fma_f32 v[14:15], v[30:31], v[8:9], v[14:15]
	v_pk_fma_f32 v[16:17], v[32:33], v[8:9], v[16:17]
	v_pk_fma_f32 v[18:19], v[34:35], v[8:9], v[18:19]
	v_pk_fma_f32 v[20:21], v[36:37], v[8:9], v[20:21]
	v_pk_fma_f32 v[22:23], v[38:39], v[8:9], v[22:23]
	v_pk_fma_f32 v[24:25], v[40:41], v[8:9], v[24:25]
	v_lshl_add_u32 v68, v84, 10, v4
	v_lshl_add_u32 v69, v85, 10, v4
	v_lshl_add_u32 v70, v86, 10, v4
	v_lshl_add_u32 v71, v87, 10, v4
	v_lshl_add_u32 v72, v88, 10, v4
	v_lshl_add_u32 v73, v89, 10, v4
	v_lshl_add_u32 v74, v90, 10, v4
	v_lshl_add_u32 v75, v91, 10, v4
	v_lshl_add_u32 v76, v92, 10, v4
	v_lshl_add_u32 v77, v93, 10, v4
	v_lshl_add_u32 v78, v94, 10, v4
	v_lshl_add_u32 v79, v95, 10, v4
	v_lshl_add_u32 v80, v96, 10, v4
	v_lshl_add_u32 v81, v97, 10, v4
	v_lshl_add_u32 v82, v98, 10, v4
	v_lshl_add_u32 v83, v99, 10, v4
	s_add_u32 s9, s22, 1
	s_and_b32 s10, s9, 7
	s_lshr_b32 s11, s9, 3
	s_mul_i32 s23, s10, s21
	s_lshl_b32 s11, s11, 7
	s_add_u32 s16, s60, s23
	s_addc_u32 s17, s61, 0
	s_add_u32 s16, s16, s11
	s_addc_u32 s17, s17, 0
	s_add_u32 s18, s16, 0x1100000
	s_addc_u32 s19, s17, 0
	s_add_u32 s12, s56, s11
	s_addc_u32 s13, s57, 0
	s_add_u32 s9, s22, 2
	s_and_b32 s9, s9, 7
	s_mul_i32 s9, s9, s20
	s_add_u32 s14, s58, s9
	s_addc_u32 s15, s59, 0
	global_load_dwordx4 v[180:183], v4, s[16:17]
	global_load_dwordx4 v[184:187], v4, s[18:19]
	global_load_dwordx4 v[84:87], v5, s[14:15] offset:0
	global_load_dwordx4 v[88:91], v5, s[14:15] offset:16
	global_load_dwordx4 v[92:95], v5, s[14:15] offset:32
	global_load_dwordx4 v[96:99], v5, s[14:15] offset:48
	s_waitcnt vmcnt(20)
	v_cvt_pk_f32_fp8_e32 v[26:27], v120
	v_cvt_pk_f32_fp8_sdwa v[28:29], v120 src0_sel:WORD_1
	v_cvt_pk_f32_fp8_e32 v[30:31], v121
	v_cvt_pk_f32_fp8_sdwa v[32:33], v121 src0_sel:WORD_1
	v_cvt_pk_f32_fp8_e32 v[34:35], v122
	v_cvt_pk_f32_fp8_sdwa v[36:37], v122 src0_sel:WORD_1
	v_cvt_pk_f32_fp8_e32 v[38:39], v123
	v_cvt_pk_f32_fp8_sdwa v[40:41], v123 src0_sel:WORD_1
	v_cvt_pk_f32_fp8_e32 v[42:43], v124
	v_cvt_pk_f32_fp8_sdwa v[44:45], v124 src0_sel:WORD_1
	v_cvt_pk_f32_fp8_e32 v[46:47], v125
	v_cvt_pk_f32_fp8_sdwa v[48:49], v125 src0_sel:WORD_1
	v_cvt_pk_f32_fp8_e32 v[50:51], v126
	v_cvt_pk_f32_fp8_sdwa v[52:53], v126 src0_sel:WORD_1
	v_cvt_pk_f32_fp8_e32 v[54:55], v127
	v_cvt_pk_f32_fp8_sdwa v[56:57], v127 src0_sel:WORD_1
	global_load_dwordx4 v[120:123], v68, s[12:13]
	global_load_dwordx4 v[124:127], v69, s[12:13]
	v_pk_mul_f32 v[58:59], v[26:27], v[10:11]
	v_pk_mul_f32 v[60:61], v[42:43], v[10:11]
	v_pk_fma_f32 v[58:59], v[28:29], v[12:13], v[58:59]
	v_pk_fma_f32 v[60:61], v[44:45], v[12:13], v[60:61]
	v_pk_fma_f32 v[58:59], v[30:31], v[14:15], v[58:59]
	v_pk_fma_f32 v[60:61], v[46:47], v[14:15], v[60:61]
	v_pk_fma_f32 v[58:59], v[32:33], v[16:17], v[58:59]
	v_pk_fma_f32 v[60:61], v[48:49], v[16:17], v[60:61]
	v_pk_fma_f32 v[58:59], v[34:35], v[18:19], v[58:59]
	v_pk_fma_f32 v[60:61], v[50:51], v[18:19], v[60:61]
	v_pk_fma_f32 v[58:59], v[36:37], v[20:21], v[58:59]
	v_pk_fma_f32 v[60:61], v[52:53], v[20:21], v[60:61]
	v_pk_fma_f32 v[58:59], v[38:39], v[22:23], v[58:59]
	v_pk_fma_f32 v[60:61], v[54:55], v[22:23], v[60:61]
	v_pk_fma_f32 v[58:59], v[40:41], v[24:25], v[58:59]
	v_pk_fma_f32 v[60:61], v[56:57], v[24:25], v[60:61]
	v_add_f32_e32 v104, v58, v59
	v_add_f32_e32 v105, v60, v61
	s_waitcnt vmcnt(20)
	v_cvt_pk_f32_fp8_e32 v[26:27], v128
	v_cvt_pk_f32_fp8_sdwa v[28:29], v128 src0_sel:WORD_1
	v_cvt_pk_f32_fp8_e32 v[30:31], v129
	v_cvt_pk_f32_fp8_sdwa v[32:33], v129 src0_sel:WORD_1
	v_cvt_pk_f32_fp8_e32 v[34:35], v130
	v_cvt_pk_f32_fp8_sdwa v[36:37], v130 src0_sel:WORD_1
	v_cvt_pk_f32_fp8_e32 v[38:39], v131
	v_cvt_pk_f32_fp8_sdwa v[40:41], v131 src0_sel:WORD_1
	v_cvt_pk_f32_fp8_e32 v[42:43], v132
	v_cvt_pk_f32_fp8_sdwa v[44:45], v132 src0_sel:WORD_1
	v_cvt_pk_f32_fp8_e32 v[46:47], v133
	v_cvt_pk_f32_fp8_sdwa v[48:49], v133 src0_sel:WORD_1
	v_cvt_pk_f32_fp8_e32 v[50:51], v134
	v_cvt_pk_f32_fp8_sdwa v[52:53], v134 src0_sel:WORD_1
	v_cvt_pk_f32_fp8_e32 v[54:55], v135
	v_cvt_pk_f32_fp8_sdwa v[56:57], v135 src0_sel:WORD_1
	global_load_dwordx4 v[128:131], v70, s[12:13]
	global_load_dwordx4 v[132:135], v71, s[12:13]
	v_pk_mul_f32 v[58:59], v[26:27], v[10:11]
	v_pk_mul_f32 v[60:61], v[42:43], v[10:11]
	v_pk_fma_f32 v[58:59], v[28:29], v[12:13], v[58:59]
	v_pk_fma_f32 v[60:61], v[44:45], v[12:13], v[60:61]
	v_pk_fma_f32 v[58:59], v[30:31], v[14:15], v[58:59]
	v_pk_fma_f32 v[60:61], v[46:47], v[14:15], v[60:61]
	v_pk_fma_f32 v[58:59], v[32:33], v[16:17], v[58:59]
	v_pk_fma_f32 v[60:61], v[48:49], v[16:17], v[60:61]
	v_pk_fma_f32 v[58:59], v[34:35], v[18:19], v[58:59]
	v_pk_fma_f32 v[60:61], v[50:51], v[18:19], v[60:61]
	v_pk_fma_f32 v[58:59], v[36:37], v[20:21], v[58:59]
	v_pk_fma_f32 v[60:61], v[52:53], v[20:21], v[60:61]
	v_pk_fma_f32 v[58:59], v[38:39], v[22:23], v[58:59]
	v_pk_fma_f32 v[60:61], v[54:55], v[22:23], v[60:61]
	v_pk_fma_f32 v[58:59], v[40:41], v[24:25], v[58:59]
	v_pk_fma_f32 v[60:61], v[56:57], v[24:25], v[60:61]
	v_add_f32_e32 v106, v58, v59
	v_add_f32_e32 v107, v60, v61
	s_waitcnt vmcnt(20)
;     ...
;     for (int m = 0; m < 16; m += 2) {
;         const u32x4_t a0 = *(const u32x4_t*)(hp + m * 64), a1 = *(const u32x4_t*)(hp + m * 64 + 64);
; #pragma unroll
;         for (int t = 0; t < NTL; ++t) FP8MM(a0, b0[t], acc[t]);
;         if (m + 2 < 16) {
; #pragma unroll
;             for (int t = 0; t < NTL; ++t) b0[t] = *(const u32x4_t*)(up[t] + (m + 2) * 64);
;         }
; #pragma unroll
;         for (int t = 0; t < NTL; ++t) FP8MM(a1, b1[t], acc[t]);
;         if (m + 3 < 16) {
; #pragma unroll
;             for (int t = 0; t < NTL; ++t) b1[t] = *(const u32x4_t*)(up[t] + (m + 3) * 64);
;         }
;     }
	v_cvt_pk_f32_fp8_e32 v[26:27], v136
	v_cvt_pk_f32_fp8_sdwa v[28:29], v136 src0_sel:WORD_1
	v_cvt_pk_f32_fp8_e32 v[30:31], v137
	v_cvt_pk_f32_fp8_sdwa v[32:33], v137 src0_sel:WORD_1
	v_cvt_pk_f32_fp8_e32 v[34:35], v138
	v_cvt_pk_f32_fp8_sdwa v[36:37], v138 src0_sel:WORD_1
	v_cvt_pk_f32_fp8_e32 v[38:39], v139
	v_cvt_pk_f32_fp8_sdwa v[40:41], v139 src0_sel:WORD_1
	v_cvt_pk_f32_fp8_e32 v[42:43], v140
	v_cvt_pk_f32_fp8_sdwa v[44:45], v140 src0_sel:WORD_1
	v_cvt_pk_f32_fp8_e32 v[46:47], v141
	v_cvt_pk_f32_fp8_sdwa v[48:49], v141 src0_sel:WORD_1
	v_cvt_pk_f32_fp8_e32 v[50:51], v142
	v_cvt_pk_f32_fp8_sdwa v[52:53], v142 src0_sel:WORD_1
	v_cvt_pk_f32_fp8_e32 v[54:55], v143
	v_cvt_pk_f32_fp8_sdwa v[56:57], v143 src0_sel:WORD_1
	global_load_dwordx4 v[136:139], v72, s[12:13]
	global_load_dwordx4 v[140:143], v73, s[12:13]
	v_pk_mul_f32 v[58:59], v[26:27], v[10:11]
	v_pk_mul_f32 v[60:61], v[42:43], v[10:11]
	v_pk_fma_f32 v[58:59], v[28:29], v[12:13], v[58:59]
	v_pk_fma_f32 v[60:61], v[44:45], v[12:13], v[60:61]
	v_pk_fma_f32 v[58:59], v[30:31], v[14:15], v[58:59]
	v_pk_fma_f32 v[60:61], v[46:47], v[14:15], v[60:61]
	v_pk_fma_f32 v[58:59], v[32:33], v[16:17], v[58:59]
	v_pk_fma_f32 v[60:61], v[48:49], v[16:17], v[60:61]
	v_pk_fma_f32 v[58:59], v[34:35], v[18:19], v[58:59]
	v_pk_fma_f32 v[60:61], v[50:51], v[18:19], v[60:61]
	v_pk_fma_f32 v[58:59], v[36:37], v[20:21], v[58:59]
	v_pk_fma_f32 v[60:61], v[52:53], v[20:21], v[60:61]
	v_pk_fma_f32 v[58:59], v[38:39], v[22:23], v[58:59]
	v_pk_fma_f32 v[60:61], v[54:55], v[22:23], v[60:61]
	v_pk_fma_f32 v[58:59], v[40:41], v[24:25], v[58:59]
	v_pk_fma_f32 v[60:61], v[56:57], v[24:25], v[60:61]
	v_add_f32_e32 v108, v58, v59
	v_add_f32_e32 v109, v60, v61
	s_waitcnt vmcnt(20)
	v_cvt_pk_f32_fp8_e32 v[26:27], v144
	v_cvt_pk_f32_fp8_sdwa v[28:29], v144 src0_sel:WORD_1
	v_cvt_pk_f32_fp8_e32 v[30:31], v145
	v_cvt_pk_f32_fp8_sdwa v[32:33], v145 src0_sel:WORD_1
	v_cvt_pk_f32_fp8_e32 v[34:35], v146
	v_cvt_pk_f32_fp8_sdwa v[36:37], v146 src0_sel:WORD_1
	v_cvt_pk_f32_fp8_e32 v[38:39], v147
	v_cvt_pk_f32_fp8_sdwa v[40:41], v147 src0_sel:WORD_1
	v_cvt_pk_f32_fp8_e32 v[42:43], v148
	v_cvt_pk_f32_fp8_sdwa v[44:45], v148 src0_sel:WORD_1
	v_cvt_pk_f32_fp8_e32 v[46:47], v149
	v_cvt_pk_f32_fp8_sdwa v[48:49], v149 src0_sel:WORD_1
	v_cvt_pk_f32_fp8_e32 v[50:51], v150
	v_cvt_pk_f32_fp8_sdwa v[52:53], v150 src0_sel:WORD_1
	v_cvt_pk_f32_fp8_e32 v[54:55], v151
	v_cvt_pk_f32_fp8_sdwa v[56:57], v151 src0_sel:WORD_1
	global_load_dwordx4 v[144:147], v74, s[12:13]
	global_load_dwordx4 v[148:151], v75, s[12:13]
	v_pk_mul_f32 v[58:59], v[26:27], v[10:11]
	v_pk_mul_f32 v[60:61], v[42:43], v[10:11]
	v_pk_fma_f32 v[58:59], v[28:29], v[12:13], v[58:59]
	v_pk_fma_f32 v[60:61], v[44:45], v[12:13], v[60:61]
	v_pk_fma_f32 v[58:59], v[30:31], v[14:15], v[58:59]
	v_pk_fma_f32 v[60:61], v[46:47], v[14:15], v[60:61]
	v_pk_fma_f32 v[58:59], v[32:33], v[16:17], v[58:59]
	v_pk_fma_f32 v[60:61], v[48:49], v[16:17], v[60:61]
	v_pk_fma_f32 v[58:59], v[34:35], v[18:19], v[58:59]
	v_pk_fma_f32 v[60:61], v[50:51], v[18:19], v[60:61]
	v_pk_fma_f32 v[58:59], v[36:37], v[20:21], v[58:59]
	v_pk_fma_f32 v[60:61], v[52:53], v[20:21], v[60:61]
	v_pk_fma_f32 v[58:59], v[38:39], v[22:23], v[58:59]
	v_pk_fma_f32 v[60:61], v[54:55], v[22:23], v[60:61]
	v_pk_fma_f32 v[58:59], v[40:41], v[24:25], v[58:59]
	v_pk_fma_f32 v[60:61], v[56:57], v[24:25], v[60:61]
	v_add_f32_e32 v110, v58, v59
	v_add_f32_e32 v111, v60, v61
	s_waitcnt vmcnt(20)
	v_cvt_pk_f32_fp8_e32 v[26:27], v152
	v_cvt_pk_f32_fp8_sdwa v[28:29], v152 src0_sel:WORD_1
	v_cvt_pk_f32_fp8_e32 v[30:31], v153
	v_cvt_pk_f32_fp8_sdwa v[32:33], v153 src0_sel:WORD_1
	v_cvt_pk_f32_fp8_e32 v[34:35], v154
	v_cvt_pk_f32_fp8_sdwa v[36:37], v154 src0_sel:WORD_1
	v_cvt_pk_f32_fp8_e32 v[38:39], v155
	v_cvt_pk_f32_fp8_sdwa v[40:41], v155 src0_sel:WORD_1
	v_cvt_pk_f32_fp8_e32 v[42:43], v156
	v_cvt_pk_f32_fp8_sdwa v[44:45], v156 src0_sel:WORD_1
	v_cvt_pk_f32_fp8_e32 v[46:47], v157
	v_cvt_pk_f32_fp8_sdwa v[48:49], v157 src0_sel:WORD_1
	v_cvt_pk_f32_fp8_e32 v[50:51], v158
	v_cvt_pk_f32_fp8_sdwa v[52:53], v158 src0_sel:WORD_1
	v_cvt_pk_f32_fp8_e32 v[54:55], v159
	v_cvt_pk_f32_fp8_sdwa v[56:57], v159 src0_sel:WORD_1
	global_load_dwordx4 v[152:155], v76, s[12:13]
	global_load_dwordx4 v[156:159], v77, s[12:13]
	v_pk_mul_f32 v[58:59], v[26:27], v[10:11]
	v_pk_mul_f32 v[60:61], v[42:43], v[10:11]
	v_pk_fma_f32 v[58:59], v[28:29], v[12:13], v[58:59]
	v_pk_fma_f32 v[60:61], v[44:45], v[12:13], v[60:61]
	v_pk_fma_f32 v[58:59], v[30:31], v[14:15], v[58:59]
	v_pk_fma_f32 v[60:61], v[46:47], v[14:15], v[60:61]
	v_pk_fma_f32 v[58:59], v[32:33], v[16:17], v[58:59]
	v_pk_fma_f32 v[60:61], v[48:49], v[16:17], v[60:61]
	v_pk_fma_f32 v[58:59], v[34:35], v[18:19], v[58:59]
	v_pk_fma_f32 v[60:61], v[50:51], v[18:19], v[60:61]
	v_pk_fma_f32 v[58:59], v[36:37], v[20:21], v[58:59]
	v_pk_fma_f32 v[60:61], v[52:53], v[20:21], v[60:61]
	v_pk_fma_f32 v[58:59], v[38:39], v[22:23], v[58:59]
	v_pk_fma_f32 v[60:61], v[54:55], v[22:23], v[60:61]
	v_pk_fma_f32 v[58:59], v[40:41], v[24:25], v[58:59]
	v_pk_fma_f32 v[60:61], v[56:57], v[24:25], v[60:61]
	v_add_f32_e32 v112, v58, v59
	v_add_f32_e32 v113, v60, v61
	s_waitcnt vmcnt(20)
; DEVI float gelu_f(float x) { const float u = 0.7978845608028654f * (x + 0.044715f * x * x * x); return x * __builtin_amdgcn_rcpf(1.f + __expf(-2.f * u)); }
;     ...
;     for (int m = 0; m < 16; m += 2) {
;         const u32x4_t a0 = *(const u32x4_t*)(hp + m * 64), a1 = *(const u32x4_t*)(hp + m * 64 + 64);
; #pragma unroll
;         for (int t = 0; t < NTL; ++t) FP8MM(a0, b0[t], acc[t]);
;         if (m + 2 < 16) {
; #pragma unroll
;             for (int t = 0; t < NTL; ++t) b0[t] = *(const u32x4_t*)(up[t] + (m + 2) * 64);
;         }
; #pragma unroll
;         for (int t = 0; t < NTL; ++t) FP8MM(a1, b1[t], acc[t]);
;         if (m + 3 < 16) {
; #pragma unroll
;             for (int t = 0; t < NTL; ++t) b1[t] = *(const u32x4_t*)(up[t] + (m + 3) * 64);
;         }
;     }
;     ...
; #pragma unroll
;     for (int t = 0; t < NTL; ++t) { const float lo = __shfl_xor(acc[t][0], 32); const float dot = (acc[t][0] + lo * (1.f / 32.f)) * s_u[t];
;         if (kq == 0) pl[t * 16 + n16] = (u32x2_t){(unsigned)e[t], __float_as_uint(g[t] * gelu_f(dot) * s_v[t])}; }
	v_cvt_pk_f32_fp8_e32 v[26:27], v160
	v_cvt_pk_f32_fp8_sdwa v[28:29], v160 src0_sel:WORD_1
	v_cvt_pk_f32_fp8_e32 v[30:31], v161
	v_cvt_pk_f32_fp8_sdwa v[32:33], v161 src0_sel:WORD_1
	v_cvt_pk_f32_fp8_e32 v[34:35], v162
	v_cvt_pk_f32_fp8_sdwa v[36:37], v162 src0_sel:WORD_1
	v_cvt_pk_f32_fp8_e32 v[38:39], v163
	v_cvt_pk_f32_fp8_sdwa v[40:41], v163 src0_sel:WORD_1
	v_cvt_pk_f32_fp8_e32 v[42:43], v164
	v_cvt_pk_f32_fp8_sdwa v[44:45], v164 src0_sel:WORD_1
	v_cvt_pk_f32_fp8_e32 v[46:47], v165
	v_cvt_pk_f32_fp8_sdwa v[48:49], v165 src0_sel:WORD_1
	v_cvt_pk_f32_fp8_e32 v[50:51], v166
	v_cvt_pk_f32_fp8_sdwa v[52:53], v166 src0_sel:WORD_1
	v_cvt_pk_f32_fp8_e32 v[54:55], v167
	v_cvt_pk_f32_fp8_sdwa v[56:57], v167 src0_sel:WORD_1
	global_load_dwordx4 v[160:163], v78, s[12:13]
	global_load_dwordx4 v[164:167], v79, s[12:13]
	v_pk_mul_f32 v[58:59], v[26:27], v[10:11]
	v_pk_mul_f32 v[60:61], v[42:43], v[10:11]
	v_pk_fma_f32 v[58:59], v[28:29], v[12:13], v[58:59]
	v_pk_fma_f32 v[60:61], v[44:45], v[12:13], v[60:61]
	v_pk_fma_f32 v[58:59], v[30:31], v[14:15], v[58:59]
	v_pk_fma_f32 v[60:61], v[46:47], v[14:15], v[60:61]
	v_pk_fma_f32 v[58:59], v[32:33], v[16:17], v[58:59]
	v_pk_fma_f32 v[60:61], v[48:49], v[16:17], v[60:61]
	v_pk_fma_f32 v[58:59], v[34:35], v[18:19], v[58:59]
	v_pk_fma_f32 v[60:61], v[50:51], v[18:19], v[60:61]
	v_pk_fma_f32 v[58:59], v[36:37], v[20:21], v[58:59]
	v_pk_fma_f32 v[60:61], v[52:53], v[20:21], v[60:61]
	v_pk_fma_f32 v[58:59], v[38:39], v[22:23], v[58:59]
	v_pk_fma_f32 v[60:61], v[54:55], v[22:23], v[60:61]
	v_pk_fma_f32 v[58:59], v[40:41], v[24:25], v[58:59]
	v_pk_fma_f32 v[60:61], v[56:57], v[24:25], v[60:61]
	v_add_f32_e32 v114, v58, v59
	v_add_f32_e32 v115, v60, v61
	s_waitcnt vmcnt(20)
	v_cvt_pk_f32_fp8_e32 v[26:27], v168
	v_cvt_pk_f32_fp8_sdwa v[28:29], v168 src0_sel:WORD_1
	v_cvt_pk_f32_fp8_e32 v[30:31], v169
	v_cvt_pk_f32_fp8_sdwa v[32:33], v169 src0_sel:WORD_1
	v_cvt_pk_f32_fp8_e32 v[34:35], v170
	v_cvt_pk_f32_fp8_sdwa v[36:37], v170 src0_sel:WORD_1
	v_cvt_pk_f32_fp8_e32 v[38:39], v171
	v_cvt_pk_f32_fp8_sdwa v[40:41], v171 src0_sel:WORD_1
	v_cvt_pk_f32_fp8_e32 v[42:43], v172
	v_cvt_pk_f32_fp8_sdwa v[44:45], v172 src0_sel:WORD_1
	v_cvt_pk_f32_fp8_e32 v[46:47], v173
	v_cvt_pk_f32_fp8_sdwa v[48:49], v173 src0_sel:WORD_1
	v_cvt_pk_f32_fp8_e32 v[50:51], v174
	v_cvt_pk_f32_fp8_sdwa v[52:53], v174 src0_sel:WORD_1
	v_cvt_pk_f32_fp8_e32 v[54:55], v175
	v_cvt_pk_f32_fp8_sdwa v[56:57], v175 src0_sel:WORD_1
	global_load_dwordx4 v[168:171], v80, s[12:13]
	global_load_dwordx4 v[172:175], v81, s[12:13]
	v_pk_mul_f32 v[58:59], v[26:27], v[10:11]
	v_pk_mul_f32 v[60:61], v[42:43], v[10:11]
	v_pk_fma_f32 v[58:59], v[28:29], v[12:13], v[58:59]
	v_pk_fma_f32 v[60:61], v[44:45], v[12:13], v[60:61]
	v_pk_fma_f32 v[58:59], v[30:31], v[14:15], v[58:59]
	v_pk_fma_f32 v[60:61], v[46:47], v[14:15], v[60:61]
	v_pk_fma_f32 v[58:59], v[32:33], v[16:17], v[58:59]
	v_pk_fma_f32 v[60:61], v[48:49], v[16:17], v[60:61]
	v_pk_fma_f32 v[58:59], v[34:35], v[18:19], v[58:59]
	v_pk_fma_f32 v[60:61], v[50:51], v[18:19], v[60:61]
	v_pk_fma_f32 v[58:59], v[36:37], v[20:21], v[58:59]
	v_pk_fma_f32 v[60:61], v[52:53], v[20:21], v[60:61]
	v_pk_fma_f32 v[58:59], v[38:39], v[22:23], v[58:59]
	v_pk_fma_f32 v[60:61], v[54:55], v[22:23], v[60:61]
	v_pk_fma_f32 v[58:59], v[40:41], v[24:25], v[58:59]
	v_pk_fma_f32 v[60:61], v[56:57], v[24:25], v[60:61]
	v_add_f32_e32 v62, v58, v59
	v_add_f32_e32 v63, v60, v61
	s_waitcnt vmcnt(20)
	v_cvt_pk_f32_fp8_e32 v[26:27], v188
	v_cvt_pk_f32_fp8_sdwa v[28:29], v188 src0_sel:WORD_1
	v_cvt_pk_f32_fp8_e32 v[30:31], v189
	v_cvt_pk_f32_fp8_sdwa v[32:33], v189 src0_sel:WORD_1
	v_cvt_pk_f32_fp8_e32 v[34:35], v190
	v_cvt_pk_f32_fp8_sdwa v[36:37], v190 src0_sel:WORD_1
	v_cvt_pk_f32_fp8_e32 v[38:39], v191
	v_cvt_pk_f32_fp8_sdwa v[40:41], v191 src0_sel:WORD_1
	v_cvt_pk_f32_fp8_e32 v[42:43], v192
	v_cvt_pk_f32_fp8_sdwa v[44:45], v192 src0_sel:WORD_1
	v_cvt_pk_f32_fp8_e32 v[46:47], v193
	v_cvt_pk_f32_fp8_sdwa v[48:49], v193 src0_sel:WORD_1
	v_cvt_pk_f32_fp8_e32 v[50:51], v194
	v_cvt_pk_f32_fp8_sdwa v[52:53], v194 src0_sel:WORD_1
	v_cvt_pk_f32_fp8_e32 v[54:55], v195
	v_cvt_pk_f32_fp8_sdwa v[56:57], v195 src0_sel:WORD_1
	global_load_dwordx4 v[188:191], v82, s[12:13]
	global_load_dwordx4 v[192:195], v83, s[12:13]
	v_pk_mul_f32 v[58:59], v[26:27], v[10:11]
	v_pk_mul_f32 v[60:61], v[42:43], v[10:11]
	v_pk_fma_f32 v[58:59], v[28:29], v[12:13], v[58:59]
	v_pk_fma_f32 v[60:61], v[44:45], v[12:13], v[60:61]
	v_pk_fma_f32 v[58:59], v[30:31], v[14:15], v[58:59]
	v_pk_fma_f32 v[60:61], v[46:47], v[14:15], v[60:61]
	v_pk_fma_f32 v[58:59], v[32:33], v[16:17], v[58:59]
	v_pk_fma_f32 v[60:61], v[48:49], v[16:17], v[60:61]
	v_pk_fma_f32 v[58:59], v[34:35], v[18:19], v[58:59]
	v_pk_fma_f32 v[60:61], v[50:51], v[18:19], v[60:61]
	v_pk_fma_f32 v[58:59], v[36:37], v[20:21], v[58:59]
	v_pk_fma_f32 v[60:61], v[52:53], v[20:21], v[60:61]
	v_pk_fma_f32 v[58:59], v[38:39], v[22:23], v[58:59]
	v_pk_fma_f32 v[60:61], v[54:55], v[22:23], v[60:61]
	v_pk_fma_f32 v[58:59], v[40:41], v[24:25], v[58:59]
	v_pk_fma_f32 v[60:61], v[56:57], v[24:25], v[60:61]
	v_add_f32_e32 v64, v58, v59
	v_add_f32_e32 v65, v60, v61
	s_nop 1
	v_add_f32_dpp v104, v104, v104 quad_perm:[1,0,3,2] row_mask:0xf bank_mask:0xf
	v_add_f32_dpp v105, v105, v105 quad_perm:[1,0,3,2] row_mask:0xf bank_mask:0xf
	v_add_f32_dpp v106, v106, v106 quad_perm:[1,0,3,2] row_mask:0xf bank_mask:0xf
	v_add_f32_dpp v107, v107, v107 quad_perm:[1,0,3,2] row_mask:0xf bank_mask:0xf
	v_add_f32_dpp v108, v108, v108 quad_perm:[1,0,3,2] row_mask:0xf bank_mask:0xf
	v_add_f32_dpp v109, v109, v109 quad_perm:[1,0,3,2] row_mask:0xf bank_mask:0xf
;     DEVI int* eidx() const { return (int*)(ws + WS_EIDX); }
; DEVI float gelu_f(float x) { const float u = 0.7978845608028654f * (x + 0.044715f * x * x * x); return x * __builtin_amdgcn_rcpf(1.f + __expf(-2.f * u)); }
;     ...
;     int e[NTL]; float g[NTL], s_u[NTL], s_v[NTL];
; #pragma unroll
;     for (int t = 0; t < NTL; ++t) { e[t] = eidx[(size_t)r * 128 + (tbase + t) * 16 + n16]; g[t] = gwv[(size_t)r * 128 + (tbase + t) * 16 + n16]; }
; #pragma unroll
;     for (int t = 0; t < NTL; ++t) { s_u[t] = su[e[t]]; s_v[t] = sv[e[t]]; }
;     ...
;     for (int t = 0; t < NTL; ++t) { const float lo = __shfl_xor(acc[t][0], 32); const float dot = (acc[t][0] + lo * (1.f / 32.f)) * s_u[t];
;         if (kq == 0) pl[t * 16 + n16] = (u32x2_t){(unsigned)e[t], __float_as_uint(g[t] * gelu_f(dot) * s_v[t])}; }
	v_add_f32_dpp v110, v110, v110 quad_perm:[1,0,3,2] row_mask:0xf bank_mask:0xf
	v_add_f32_dpp v111, v111, v111 quad_perm:[1,0,3,2] row_mask:0xf bank_mask:0xf
	v_add_f32_dpp v112, v112, v112 quad_perm:[1,0,3,2] row_mask:0xf bank_mask:0xf
	v_add_f32_dpp v113, v113, v113 quad_perm:[1,0,3,2] row_mask:0xf bank_mask:0xf
	v_add_f32_dpp v114, v114, v114 quad_perm:[1,0,3,2] row_mask:0xf bank_mask:0xf
	v_add_f32_dpp v115, v115, v115 quad_perm:[1,0,3,2] row_mask:0xf bank_mask:0xf
	v_add_f32_dpp v62, v62, v62 quad_perm:[1,0,3,2] row_mask:0xf bank_mask:0xf
	v_add_f32_dpp v63, v63, v63 quad_perm:[1,0,3,2] row_mask:0xf bank_mask:0xf
	v_add_f32_dpp v64, v64, v64 quad_perm:[1,0,3,2] row_mask:0xf bank_mask:0xf
	v_add_f32_dpp v65, v65, v65 quad_perm:[1,0,3,2] row_mask:0xf bank_mask:0xf
	v_add_f32_dpp v104, v104, v104 quad_perm:[2,3,0,1] row_mask:0xf bank_mask:0xf
	v_add_f32_dpp v105, v105, v105 quad_perm:[2,3,0,1] row_mask:0xf bank_mask:0xf
	v_add_f32_dpp v106, v106, v106 quad_perm:[2,3,0,1] row_mask:0xf bank_mask:0xf
	v_add_f32_dpp v107, v107, v107 quad_perm:[2,3,0,1] row_mask:0xf bank_mask:0xf
	v_add_f32_dpp v108, v108, v108 quad_perm:[2,3,0,1] row_mask:0xf bank_mask:0xf
	v_add_f32_dpp v109, v109, v109 quad_perm:[2,3,0,1] row_mask:0xf bank_mask:0xf
	v_add_f32_dpp v110, v110, v110 quad_perm:[2,3,0,1] row_mask:0xf bank_mask:0xf
	v_add_f32_dpp v111, v111, v111 quad_perm:[2,3,0,1] row_mask:0xf bank_mask:0xf
	v_add_f32_dpp v112, v112, v112 quad_perm:[2,3,0,1] row_mask:0xf bank_mask:0xf
	v_add_f32_dpp v113, v113, v113 quad_perm:[2,3,0,1] row_mask:0xf bank_mask:0xf
	v_add_f32_dpp v114, v114, v114 quad_perm:[2,3,0,1] row_mask:0xf bank_mask:0xf
	v_add_f32_dpp v115, v115, v115 quad_perm:[2,3,0,1] row_mask:0xf bank_mask:0xf
	v_add_f32_dpp v62, v62, v62 quad_perm:[2,3,0,1] row_mask:0xf bank_mask:0xf
	v_add_f32_dpp v63, v63, v63 quad_perm:[2,3,0,1] row_mask:0xf bank_mask:0xf
	v_add_f32_dpp v64, v64, v64 quad_perm:[2,3,0,1] row_mask:0xf bank_mask:0xf
	v_add_f32_dpp v65, v65, v65 quad_perm:[2,3,0,1] row_mask:0xf bank_mask:0xf
	v_add_f32_dpp v104, v104, v104 row_half_mirror row_mask:0xf bank_mask:0xf
	v_add_f32_dpp v105, v105, v105 row_half_mirror row_mask:0xf bank_mask:0xf
	v_add_f32_dpp v106, v106, v106 row_half_mirror row_mask:0xf bank_mask:0xf
	v_add_f32_dpp v107, v107, v107 row_half_mirror row_mask:0xf bank_mask:0xf
	v_add_f32_dpp v108, v108, v108 row_half_mirror row_mask:0xf bank_mask:0xf
	v_add_f32_dpp v109, v109, v109 row_half_mirror row_mask:0xf bank_mask:0xf
	v_add_f32_dpp v110, v110, v110 row_half_mirror row_mask:0xf bank_mask:0xf
	v_add_f32_dpp v111, v111, v111 row_half_mirror row_mask:0xf bank_mask:0xf
	v_add_f32_dpp v112, v112, v112 row_half_mirror row_mask:0xf bank_mask:0xf
	v_add_f32_dpp v113, v113, v113 row_half_mirror row_mask:0xf bank_mask:0xf
	v_add_f32_dpp v114, v114, v114 row_half_mirror row_mask:0xf bank_mask:0xf
	v_add_f32_dpp v115, v115, v115 row_half_mirror row_mask:0xf bank_mask:0xf
	v_add_f32_dpp v62, v62, v62 row_half_mirror row_mask:0xf bank_mask:0xf
	v_add_f32_dpp v63, v63, v63 row_half_mirror row_mask:0xf bank_mask:0xf
	v_add_f32_dpp v64, v64, v64 row_half_mirror row_mask:0xf bank_mask:0xf
	v_add_f32_dpp v65, v65, v65 row_half_mirror row_mask:0xf bank_mask:0xf
	v_cndmask_b32_e64 v118, v118, v104, s[24:25]
	v_cndmask_b32_e64 v119, v119, v105, s[24:25]
	v_cndmask_b32_e64 v118, v118, v106, s[26:27]
	v_cndmask_b32_e64 v119, v119, v107, s[26:27]
	v_cndmask_b32_e64 v118, v118, v108, s[28:29]
	v_cndmask_b32_e64 v119, v119, v109, s[28:29]
	v_cndmask_b32_e64 v118, v118, v110, s[30:31]
	v_cndmask_b32_e64 v119, v119, v111, s[30:31]
	v_cndmask_b32_e64 v118, v118, v112, s[40:41]
	v_cndmask_b32_e64 v119, v119, v113, s[40:41]
	v_cndmask_b32_e64 v118, v118, v114, s[42:43]
	v_cndmask_b32_e64 v119, v119, v115, s[42:43]
	v_cndmask_b32_e64 v118, v118, v62, s[44:45]
	v_cndmask_b32_e64 v119, v119, v63, s[44:45]
	v_cndmask_b32_e64 v118, v118, v64, s[54:55]
	v_cndmask_b32_e64 v119, v119, v65, s[54:55]
	s_and_b32 s9, s22, 7
	s_lshl_b32 s9, s9, 10
	v_add_u32_e32 v7, s9, v6
	ds_add_f32 v7, v118 offset:4
	ds_add_f32 v7, v119 offset:12
	s_add_u32 s22, s22, 1
	s_cmp_lg_u32 s22, 64
	s_cbranch_scc1 .Lg1_loop
	s_waitcnt vmcnt(0) lgkmcnt(0)
	s_lshl_b32 s9, s48, 9
	s_lshl_b32 s20, s34, 9
	s_add_u32 s10, s6, 0x1b292100
	s_addc_u32 s11, s7, 0
	s_add_u32 s10, s10, s9
	s_addc_u32 s11, s11, 0
	s_add_u32 s12, s6, 0x1bb12100
	s_addc_u32 s13, s7, 0
	s_add_u32 s12, s12, s9
	s_addc_u32 s13, s13, 0
	s_lshl_b32 s9, s8, 16
	s_add_u32 s16, s6, 0x2fa42100
	s_addc_u32 s17, s7, 0
	s_add_u32 s16, s16, s9
	s_addc_u32 s17, s17, 0
	s_add_u32 s18, s16, 0x40000
	s_addc_u32 s19, s17, 0
	v_lshlrev_b32_e32 v2, 3, v1
	v_lshl_add_u32 v3, v1, 4, s85
	ds_read_b128 v[68:71], v3 offset:0
	ds_read_b128 v[72:75], v3 offset:1024
	ds_read_b128 v[76:79], v3 offset:2048
	ds_read_b128 v[80:83], v3 offset:3072
	ds_read_b128 v[84:87], v3 offset:4096
	ds_read_b128 v[88:91], v3 offset:5120
	ds_read_b128 v[92:95], v3 offset:6144
	ds_read_b128 v[96:99], v3 offset:7168
	global_load_dwordx2 v[20:21], v2, s[10:11]
	global_load_dwordx2 v[22:23], v2, s[12:13]
	s_add_u32 s10, s10, s20
	s_addc_u32 s11, s11, 0
	s_add_u32 s12, s12, s20
	s_addc_u32 s13, s13, 0
	global_load_dwordx2 v[24:25], v2, s[10:11]
	global_load_dwordx2 v[26:27], v2, s[12:13]
	s_add_u32 s10, s10, s20
	s_addc_u32 s11, s11, 0
	s_add_u32 s12, s12, s20
	s_addc_u32 s13, s13, 0
	global_load_dwordx2 v[28:29], v2, s[10:11]
	global_load_dwordx2 v[30:31], v2, s[12:13]
	s_add_u32 s10, s10, s20
	s_addc_u32 s11, s11, 0
	s_add_u32 s12, s12, s20
	s_addc_u32 s13, s13, 0
	global_load_dwordx2 v[32:33], v2, s[10:11]
	global_load_dwordx2 v[34:35], v2, s[12:13]
	s_add_u32 s10, s10, s20
	s_addc_u32 s11, s11, 0
	s_add_u32 s12, s12, s20
	s_addc_u32 s13, s13, 0
	global_load_dwordx2 v[36:37], v2, s[10:11]
	global_load_dwordx2 v[38:39], v2, s[12:13]
	s_add_u32 s10, s10, s20
	s_addc_u32 s11, s11, 0
	s_add_u32 s12, s12, s20
	s_addc_u32 s13, s13, 0
	global_load_dwordx2 v[40:41], v2, s[10:11]
	global_load_dwordx2 v[42:43], v2, s[12:13]
	s_add_u32 s10, s10, s20
	s_addc_u32 s11, s11, 0
	s_add_u32 s12, s12, s20
	s_addc_u32 s13, s13, 0
	global_load_dwordx2 v[44:45], v2, s[10:11]
	global_load_dwordx2 v[46:47], v2, s[12:13]
	s_add_u32 s10, s10, s20
	s_addc_u32 s11, s11, 0
	s_add_u32 s12, s12, s20
	s_addc_u32 s13, s13, 0
	global_load_dwordx2 v[48:49], v2, s[10:11]
	global_load_dwordx2 v[50:51], v2, s[12:13]
	s_add_u32 s10, s10, s20
	s_addc_u32 s11, s11, 0
	s_add_u32 s12, s12, s20
	s_addc_u32 s13, s13, 0
	s_waitcnt vmcnt(15)
;     DEVI int* eidx() const { return (int*)(ws + WS_EIDX); }
; DEVI float gelu_f(float x) { const float u = 0.7978845608028654f * (x + 0.044715f * x * x * x); return x * __builtin_amdgcn_rcpf(1.f + __expf(-2.f * u)); }
;     ...
;     for (int t = 0; t < NTL; ++t) { e[t] = eidx[(size_t)r * 128 + (tbase + t) * 16 + n16]; g[t] = gwv[(size_t)r * 128 + (tbase + t) * 16 + n16]; }
; #pragma unroll
;     for (int t = 0; t < NTL; ++t) { s_u[t] = su[e[t]]; s_v[t] = sv[e[t]]; }
;     ...
;     for (int t = 0; t < NTL; ++t) { const float lo = __shfl_xor(acc[t][0], 32); const float dot = (acc[t][0] + lo * (1.f / 32.f)) * s_u[t];
;         if (kq == 0) pl[t * 16 + n16] = (u32x2_t){(unsigned)e[t], __float_as_uint(g[t] * gelu_f(dot) * s_v[t])}; }
	v_lshlrev_b32_e32 v4, 2, v20
	v_lshlrev_b32_e32 v5, 2, v21
	global_load_dword v120, v4, s[16:17]
	global_load_dword v121, v5, s[16:17]
	global_load_dword v122, v4, s[18:19]
	global_load_dword v123, v5, s[18:19]
	s_waitcnt vmcnt(17)
	v_lshlrev_b32_e32 v4, 2, v24
	v_lshlrev_b32_e32 v5, 2, v25
	global_load_dword v124, v4, s[16:17]
	global_load_dword v125, v5, s[16:17]
	global_load_dword v126, v4, s[18:19]
	global_load_dword v127, v5, s[18:19]
	s_waitcnt vmcnt(19)
	v_lshlrev_b32_e32 v4, 2, v28
	v_lshlrev_b32_e32 v5, 2, v29
	global_load_dword v128, v4, s[16:17]
	global_load_dword v129, v5, s[16:17]
	global_load_dword v130, v4, s[18:19]
	global_load_dword v131, v5, s[18:19]
	s_waitcnt vmcnt(21)
	v_lshlrev_b32_e32 v4, 2, v32
	v_lshlrev_b32_e32 v5, 2, v33
	global_load_dword v132, v4, s[16:17]
	global_load_dword v133, v5, s[16:17]
	global_load_dword v134, v4, s[18:19]
	global_load_dword v135, v5, s[18:19]
	s_waitcnt vmcnt(23)
	v_lshlrev_b32_e32 v4, 2, v36
	v_lshlrev_b32_e32 v5, 2, v37
	global_load_dword v136, v4, s[16:17]
	global_load_dword v137, v5, s[16:17]
	global_load_dword v138, v4, s[18:19]
	global_load_dword v139, v5, s[18:19]
	s_waitcnt vmcnt(25)
	v_lshlrev_b32_e32 v4, 2, v40
	v_lshlrev_b32_e32 v5, 2, v41
	global_load_dword v140, v4, s[16:17]
	global_load_dword v141, v5, s[16:17]
	global_load_dword v142, v4, s[18:19]
	global_load_dword v143, v5, s[18:19]
	s_waitcnt vmcnt(27)
	v_lshlrev_b32_e32 v4, 2, v44
	v_lshlrev_b32_e32 v5, 2, v45
	global_load_dword v144, v4, s[16:17]
	global_load_dword v145, v5, s[16:17]
	global_load_dword v146, v4, s[18:19]
	global_load_dword v147, v5, s[18:19]
	s_waitcnt vmcnt(29)
	v_lshlrev_b32_e32 v4, 2, v48
	v_lshlrev_b32_e32 v5, 2, v49
	global_load_dword v148, v4, s[16:17]
	global_load_dword v149, v5, s[16:17]
	global_load_dword v150, v4, s[18:19]
	global_load_dword v151, v5, s[18:19]
	s_waitcnt lgkmcnt(0)
	s_waitcnt vmcnt(28)
	v_mul_f32_e32 v69, v69, v120
	v_mul_f32_e32 v6, 0x3d372713, v69
	v_mul_f32_e32 v6, v69, v6
	v_fma_f32 v6, v69, v6, v69
	v_mul_f32_e32 v6, 0x3f4c422a, v6
	v_mul_f32_e32 v6, -2.0, v6
	v_mul_f32_e32 v6, 0x3fb8aa3b, v6
	v_exp_f32_e32 v6, v6
	s_nop 0
	v_add_f32_e32 v6, 1.0, v6
	v_rcp_f32_e32 v6, v6
	s_nop 0
	v_mul_f32_e32 v69, v69, v6
	v_mul_f32_e32 v69, v22, v69
	v_mul_f32_e32 v69, v122, v69
	v_mul_f32_e32 v71, v71, v121
	v_mul_f32_e32 v7, 0x3d372713, v71
	v_mul_f32_e32 v7, v71, v7
	v_fma_f32 v7, v71, v7, v71
	v_mul_f32_e32 v7, 0x3f4c422a, v7
	v_mul_f32_e32 v7, -2.0, v7
	v_mul_f32_e32 v7, 0x3fb8aa3b, v7
	v_exp_f32_e32 v7, v7
	s_nop 0
	v_add_f32_e32 v7, 1.0, v7
	v_rcp_f32_e32 v7, v7
	s_nop 0
	v_mul_f32_e32 v71, v71, v7
	v_mul_f32_e32 v71, v23, v71
	v_mul_f32_e32 v71, v123, v71
	v_mov_b32_e32 v68, v20
	v_mov_b32_e32 v70, v21
	ds_write_b128 v3, v[68:71] offset:0
	s_waitcnt vmcnt(24)
	v_mul_f32_e32 v73, v73, v124
	v_mul_f32_e32 v6, 0x3d372713, v73
	v_mul_f32_e32 v6, v73, v6
	v_fma_f32 v6, v73, v6, v73
	v_mul_f32_e32 v6, 0x3f4c422a, v6
	v_mul_f32_e32 v6, -2.0, v6
	v_mul_f32_e32 v6, 0x3fb8aa3b, v6
	v_exp_f32_e32 v6, v6
	s_nop 0
	v_add_f32_e32 v6, 1.0, v6
	v_rcp_f32_e32 v6, v6
	s_nop 0
	v_mul_f32_e32 v73, v73, v6
	v_mul_f32_e32 v73, v26, v73
	v_mul_f32_e32 v73, v126, v73
	v_mul_f32_e32 v75, v75, v125
	v_mul_f32_e32 v7, 0x3d372713, v75
	v_mul_f32_e32 v7, v75, v7
	v_fma_f32 v7, v75, v7, v75
	v_mul_f32_e32 v7, 0x3f4c422a, v7
	v_mul_f32_e32 v7, -2.0, v7
	v_mul_f32_e32 v7, 0x3fb8aa3b, v7
	v_exp_f32_e32 v7, v7
	s_nop 0
	v_add_f32_e32 v7, 1.0, v7
	v_rcp_f32_e32 v7, v7
	s_nop 0
	v_mul_f32_e32 v75, v75, v7
	v_mul_f32_e32 v75, v27, v75
	v_mul_f32_e32 v75, v127, v75
	v_mov_b32_e32 v72, v24
	v_mov_b32_e32 v74, v25
	ds_write_b128 v3, v[72:75] offset:1024
	s_waitcnt vmcnt(20)
	v_mul_f32_e32 v77, v77, v128
	v_mul_f32_e32 v6, 0x3d372713, v77
	v_mul_f32_e32 v6, v77, v6
	v_fma_f32 v6, v77, v6, v77
	v_mul_f32_e32 v6, 0x3f4c422a, v6
	v_mul_f32_e32 v6, -2.0, v6
	v_mul_f32_e32 v6, 0x3fb8aa3b, v6
	v_exp_f32_e32 v6, v6
	s_nop 0
	v_add_f32_e32 v6, 1.0, v6
	v_rcp_f32_e32 v6, v6
	s_nop 0
	v_mul_f32_e32 v77, v77, v6
	v_mul_f32_e32 v77, v30, v77
	v_mul_f32_e32 v77, v130, v77
	v_mul_f32_e32 v79, v79, v129
	v_mul_f32_e32 v7, 0x3d372713, v79
	v_mul_f32_e32 v7, v79, v7
	v_fma_f32 v7, v79, v7, v79
	v_mul_f32_e32 v7, 0x3f4c422a, v7
	v_mul_f32_e32 v7, -2.0, v7
	v_mul_f32_e32 v7, 0x3fb8aa3b, v7
	v_exp_f32_e32 v7, v7
	s_nop 0
	v_add_f32_e32 v7, 1.0, v7
	v_rcp_f32_e32 v7, v7
	s_nop 0
	v_mul_f32_e32 v79, v79, v7
	v_mul_f32_e32 v79, v31, v79
	v_mul_f32_e32 v79, v131, v79
	v_mov_b32_e32 v76, v28
	v_mov_b32_e32 v78, v29
	ds_write_b128 v3, v[76:79] offset:2048
	s_waitcnt vmcnt(16)
	v_mul_f32_e32 v81, v81, v132
	v_mul_f32_e32 v6, 0x3d372713, v81
	v_mul_f32_e32 v6, v81, v6
	v_fma_f32 v6, v81, v6, v81
	v_mul_f32_e32 v6, 0x3f4c422a, v6
	v_mul_f32_e32 v6, -2.0, v6
	v_mul_f32_e32 v6, 0x3fb8aa3b, v6
	v_exp_f32_e32 v6, v6
	s_nop 0
	v_add_f32_e32 v6, 1.0, v6
	v_rcp_f32_e32 v6, v6
	s_nop 0
	v_mul_f32_e32 v81, v81, v6
	v_mul_f32_e32 v81, v34, v81
	v_mul_f32_e32 v81, v134, v81
	v_mul_f32_e32 v83, v83, v133
	v_mul_f32_e32 v7, 0x3d372713, v83
	v_mul_f32_e32 v7, v83, v7
	v_fma_f32 v7, v83, v7, v83
	v_mul_f32_e32 v7, 0x3f4c422a, v7
	v_mul_f32_e32 v7, -2.0, v7
	v_mul_f32_e32 v7, 0x3fb8aa3b, v7
	v_exp_f32_e32 v7, v7
	s_nop 0
	v_add_f32_e32 v7, 1.0, v7
	v_rcp_f32_e32 v7, v7
	s_nop 0
	v_mul_f32_e32 v83, v83, v7
	v_mul_f32_e32 v83, v35, v83
	v_mul_f32_e32 v83, v135, v83
	v_mov_b32_e32 v80, v32
	v_mov_b32_e32 v82, v33
	ds_write_b128 v3, v[80:83] offset:3072
	s_waitcnt vmcnt(12)
; DEVI float gelu_f(float x) { const float u = 0.7978845608028654f * (x + 0.044715f * x * x * x); return x * __builtin_amdgcn_rcpf(1.f + __expf(-2.f * u)); }
;     ...
;     for (int t = 0; t < NTL; ++t) { const float lo = __shfl_xor(acc[t][0], 32); const float dot = (acc[t][0] + lo * (1.f / 32.f)) * s_u[t];
;         if (kq == 0) pl[t * 16 + n16] = (u32x2_t){(unsigned)e[t], __float_as_uint(g[t] * gelu_f(dot) * s_v[t])}; }
;     ...
;     for (int j0 = 0; j0 < NTL * 16; j0 += 16) {
;         u32x4_t w[16]; float cj[16];
; #pragma unroll
;         for (int jj = 0; jj < 16; ++jj) { const u32x2_t pr = pl[j0 + jj]; const int ej = __builtin_amdgcn_readfirstlane((int)pr.x); cj[jj] = __uint_as_float(pr.y);
;             w[jj] = *(const u32x4_t*)(v8 + (size_t)ej * D + 16 * lane); }
; #pragma unroll
;         for (int jj = 0; jj < 16; ++jj) { const float c = cj[jj];
; #pragma unroll
;             for (int q = 0; q < 4; ++q) { const f32x2_t lo = __builtin_amdgcn_cvt_pk_f32_fp8((int)w[jj][q], false), hi = __builtin_amdgcn_cvt_pk_f32_fp8((int)w[jj][q], true);
;                 o[4 * q] += c * lo[0]; o[4 * q + 1] += c * lo[1]; o[4 * q + 2] += c * hi[0]; o[4 * q + 3] += c * hi[1]; } }
	v_mul_f32_e32 v85, v85, v136
	v_mul_f32_e32 v6, 0x3d372713, v85
	v_mul_f32_e32 v6, v85, v6
	v_fma_f32 v6, v85, v6, v85
	v_mul_f32_e32 v6, 0x3f4c422a, v6
	v_mul_f32_e32 v6, -2.0, v6
	v_mul_f32_e32 v6, 0x3fb8aa3b, v6
	v_exp_f32_e32 v6, v6
	s_nop 0
	v_add_f32_e32 v6, 1.0, v6
	v_rcp_f32_e32 v6, v6
	s_nop 0
	v_mul_f32_e32 v85, v85, v6
	v_mul_f32_e32 v85, v38, v85
	v_mul_f32_e32 v85, v138, v85
	v_mul_f32_e32 v87, v87, v137
	v_mul_f32_e32 v7, 0x3d372713, v87
	v_mul_f32_e32 v7, v87, v7
	v_fma_f32 v7, v87, v7, v87
	v_mul_f32_e32 v7, 0x3f4c422a, v7
	v_mul_f32_e32 v7, -2.0, v7
	v_mul_f32_e32 v7, 0x3fb8aa3b, v7
	v_exp_f32_e32 v7, v7
	s_nop 0
	v_add_f32_e32 v7, 1.0, v7
	v_rcp_f32_e32 v7, v7
	s_nop 0
	v_mul_f32_e32 v87, v87, v7
	v_mul_f32_e32 v87, v39, v87
	v_mul_f32_e32 v87, v139, v87
	v_mov_b32_e32 v84, v36
	v_mov_b32_e32 v86, v37
	ds_write_b128 v3, v[84:87] offset:4096
	s_waitcnt vmcnt(8)
	v_mul_f32_e32 v89, v89, v140
	v_mul_f32_e32 v6, 0x3d372713, v89
	v_mul_f32_e32 v6, v89, v6
	v_fma_f32 v6, v89, v6, v89
	v_mul_f32_e32 v6, 0x3f4c422a, v6
	v_mul_f32_e32 v6, -2.0, v6
	v_mul_f32_e32 v6, 0x3fb8aa3b, v6
	v_exp_f32_e32 v6, v6
	s_nop 0
	v_add_f32_e32 v6, 1.0, v6
	v_rcp_f32_e32 v6, v6
	s_nop 0
	v_mul_f32_e32 v89, v89, v6
	v_mul_f32_e32 v89, v42, v89
	v_mul_f32_e32 v89, v142, v89
	v_mul_f32_e32 v91, v91, v141
	v_mul_f32_e32 v7, 0x3d372713, v91
	v_mul_f32_e32 v7, v91, v7
	v_fma_f32 v7, v91, v7, v91
	v_mul_f32_e32 v7, 0x3f4c422a, v7
	v_mul_f32_e32 v7, -2.0, v7
	v_mul_f32_e32 v7, 0x3fb8aa3b, v7
	v_exp_f32_e32 v7, v7
	s_nop 0
	v_add_f32_e32 v7, 1.0, v7
	v_rcp_f32_e32 v7, v7
	s_nop 0
	v_mul_f32_e32 v91, v91, v7
	v_mul_f32_e32 v91, v43, v91
	v_mul_f32_e32 v91, v143, v91
	v_mov_b32_e32 v88, v40
	v_mov_b32_e32 v90, v41
	ds_write_b128 v3, v[88:91] offset:5120
	s_waitcnt vmcnt(4)
	v_mul_f32_e32 v93, v93, v144
	v_mul_f32_e32 v6, 0x3d372713, v93
	v_mul_f32_e32 v6, v93, v6
	v_fma_f32 v6, v93, v6, v93
	v_mul_f32_e32 v6, 0x3f4c422a, v6
	v_mul_f32_e32 v6, -2.0, v6
	v_mul_f32_e32 v6, 0x3fb8aa3b, v6
	v_exp_f32_e32 v6, v6
	s_nop 0
	v_add_f32_e32 v6, 1.0, v6
	v_rcp_f32_e32 v6, v6
	s_nop 0
	v_mul_f32_e32 v93, v93, v6
	v_mul_f32_e32 v93, v46, v93
	v_mul_f32_e32 v93, v146, v93
	v_mul_f32_e32 v95, v95, v145
	v_mul_f32_e32 v7, 0x3d372713, v95
	v_mul_f32_e32 v7, v95, v7
	v_fma_f32 v7, v95, v7, v95
	v_mul_f32_e32 v7, 0x3f4c422a, v7
	v_mul_f32_e32 v7, -2.0, v7
	v_mul_f32_e32 v7, 0x3fb8aa3b, v7
	v_exp_f32_e32 v7, v7
	s_nop 0
	v_add_f32_e32 v7, 1.0, v7
	v_rcp_f32_e32 v7, v7
	s_nop 0
	v_mul_f32_e32 v95, v95, v7
	v_mul_f32_e32 v95, v47, v95
	v_mul_f32_e32 v95, v147, v95
	v_mov_b32_e32 v92, v44
	v_mov_b32_e32 v94, v45
	ds_write_b128 v3, v[92:95] offset:6144
	s_waitcnt vmcnt(0)
	v_mul_f32_e32 v97, v97, v148
	v_mul_f32_e32 v6, 0x3d372713, v97
	v_mul_f32_e32 v6, v97, v6
	v_fma_f32 v6, v97, v6, v97
	v_mul_f32_e32 v6, 0x3f4c422a, v6
	v_mul_f32_e32 v6, -2.0, v6
	v_mul_f32_e32 v6, 0x3fb8aa3b, v6
	v_exp_f32_e32 v6, v6
	s_nop 0
	v_add_f32_e32 v6, 1.0, v6
	v_rcp_f32_e32 v6, v6
	s_nop 0
	v_mul_f32_e32 v97, v97, v6
	v_mul_f32_e32 v97, v50, v97
	v_mul_f32_e32 v97, v150, v97
	v_mul_f32_e32 v99, v99, v149
	v_mul_f32_e32 v7, 0x3d372713, v99
	v_mul_f32_e32 v7, v99, v7
	v_fma_f32 v7, v99, v7, v99
	v_mul_f32_e32 v7, 0x3f4c422a, v7
	v_mul_f32_e32 v7, -2.0, v7
	v_mul_f32_e32 v7, 0x3fb8aa3b, v7
	v_exp_f32_e32 v7, v7
	s_nop 0
	v_add_f32_e32 v7, 1.0, v7
	v_rcp_f32_e32 v7, v7
	s_nop 0
	v_mul_f32_e32 v99, v99, v7
	v_mul_f32_e32 v99, v51, v99
	v_mul_f32_e32 v99, v151, v99
	v_mov_b32_e32 v96, v48
	v_mov_b32_e32 v98, v49
	ds_write_b128 v3, v[96:99] offset:7168
	s_waitcnt lgkmcnt(0)
	v_cmp_gt_u32_e32 vcc, 8, v116
	s_nop 1
	s_lshl_b32 s20, s34, 12
	s_lshl_b32 s11, s8, 24
	s_add_u32 s56, s6, 0x27a42100
	s_addc_u32 s57, s7, 0
	s_add_u32 s56, s56, s11
	s_addc_u32 s57, s57, 0
	s_mov_b32 s12, s56
	s_mov_b32 s13, s57
	s_lshl_b32 s11, s48, 12
	s_add_u32 s58, s4, s11
	s_addc_u32 s59, s5, 0
	s_mul_i32 s11, s8, 0x6c000
	s_add_u32 s60, s6, 0x9000
	s_addc_u32 s61, s7, 0
	s_add_u32 s60, s60, s11
	s_addc_u32 s61, s61, 0
	s_mov_b32 s24, 0xff00ff00
	s_mov_b32 s25, 0xff00ff00
	v_and_b32_e32 v2, 7, v1
	v_lshrrev_b32_e32 v3, 3, v1
	v_lshlrev_b32_e32 v4, 4, v2
	v_lshlrev_b32_e32 v5, 7, v3
	v_add_u32_e32 v5, s85, v5
	v_lshlrev_b32_e32 v6, 6, v2
	v_lshl_add_u32 v6, v3, 3, v6
	ds_read_b128 v[26:29], v5 offset:0
	ds_read_b128 v[30:33], v5 offset:16
	ds_read_b128 v[34:37], v5 offset:32
	ds_read_b128 v[38:41], v5 offset:48
	ds_read_b128 v[42:45], v5 offset:64
	ds_read_b128 v[46:49], v5 offset:80
	ds_read_b128 v[50:53], v5 offset:96
	ds_read_b128 v[54:57], v5 offset:112
	s_waitcnt lgkmcnt(0)
	v_lshl_add_u32 v68, v26, 10, v4
	v_lshl_add_u32 v69, v28, 10, v4
	v_lshl_add_u32 v70, v30, 10, v4
	v_lshl_add_u32 v71, v32, 10, v4
	v_lshl_add_u32 v72, v34, 10, v4
	v_lshl_add_u32 v73, v36, 10, v4
	v_lshl_add_u32 v74, v38, 10, v4
	v_lshl_add_u32 v75, v40, 10, v4
	v_lshl_add_u32 v76, v42, 10, v4
	v_lshl_add_u32 v77, v44, 10, v4
	v_lshl_add_u32 v78, v46, 10, v4
	v_lshl_add_u32 v79, v48, 10, v4
	v_lshl_add_u32 v80, v50, 10, v4
	v_lshl_add_u32 v81, v52, 10, v4
	v_lshl_add_u32 v82, v54, 10, v4
	v_lshl_add_u32 v83, v56, 10, v4
	global_load_dwordx4 v[120:123], v68, s[12:13]
	global_load_dwordx4 v[124:127], v69, s[12:13]
	global_load_dwordx4 v[128:131], v70, s[12:13]
	global_load_dwordx4 v[132:135], v71, s[12:13]
	global_load_dwordx4 v[136:139], v72, s[12:13]
	global_load_dwordx4 v[140:143], v73, s[12:13]
	global_load_dwordx4 v[144:147], v74, s[12:13]
	global_load_dwordx4 v[148:151], v75, s[12:13]
	global_load_dwordx4 v[152:155], v76, s[12:13]
	global_load_dwordx4 v[156:159], v77, s[12:13]
	global_load_dwordx4 v[160:163], v78, s[12:13]
	global_load_dwordx4 v[164:167], v79, s[12:13]
	global_load_dwordx4 v[168:171], v80, s[12:13]
	global_load_dwordx4 v[172:175], v81, s[12:13]
	global_load_dwordx4 v[188:191], v82, s[12:13]
	global_load_dwordx4 v[192:195], v83, s[12:13]
	s_mov_b32 s22, 0
;     ...
;     for (int j0 = 0; j0 < NTL * 16; j0 += 16) {
;         u32x4_t w[16]; float cj[16];
; #pragma unroll
;         for (int jj = 0; jj < 16; ++jj) { const u32x2_t pr = pl[j0 + jj]; const int ej = __builtin_amdgcn_readfirstlane((int)pr.x); cj[jj] = __uint_as_float(pr.y);
;             w[jj] = *(const u32x4_t*)(v8 + (size_t)ej * D + 16 * lane); }
; #pragma unroll
;         for (int jj = 0; jj < 16; ++jj) { const float c = cj[jj];
; #pragma unroll
;             for (int q = 0; q < 4; ++q) { const f32x2_t lo = __builtin_amdgcn_cvt_pk_f32_fp8((int)w[jj][q], false), hi = __builtin_amdgcn_cvt_pk_f32_fp8((int)w[jj][q], true);
;                 o[4 * q] += c * lo[0]; o[4 * q + 1] += c * lo[1]; o[4 * q + 2] += c * hi[0]; o[4 * q + 3] += c * hi[1]; } }
.Lg2_loop:
	s_and_b32 s9, s22, 7
	s_lshr_b32 s10, s22, 3
	s_mul_i32 s11, s9, s20
	s_lshl_b32 s23, s10, 9
	s_add_u32 s14, s58, s11
	s_addc_u32 s15, s59, 0
	s_add_u32 s14, s14, s23
	s_addc_u32 s15, s15, 0
	s_mul_i32 s11, s9, s34
	s_add_u32 s11, s11, s48
	s_lshr_b32 s11, s11, 13
	s_mul_i32 s11, s11, 0x6000
	s_add_u32 s16, s60, s11
	s_addc_u32 s17, s61, 0
	s_add_u32 s16, s16, s23
	s_addc_u32 s17, s17, 0
	global_load_dwordx2 v[58:59], v6, s[14:15]
	global_load_dwordx2 v[60:61], v6, s[16:17]
	s_lshl_b32 s9, s9, 10
	v_add_u32_e32 v7, s9, v5
	s_add_u32 s10, s22, 1
	s_and_b32 s9, s10, 7
	s_lshl_b32 s9, s9, 10
	v_add_u32_e32 v8, s9, v5
	s_lshr_b32 s10, s10, 3
	s_lshl_b32 s10, s10, 7
	s_add_u32 s12, s56, s10
	s_addc_u32 s13, s57, 0
	ds_read_b128 v[84:87], v7 offset:0
	ds_read_b128 v[88:91], v7 offset:16
	ds_read_b128 v[92:95], v7 offset:32
	ds_read_b128 v[96:99], v7 offset:48
	ds_read_b128 v[104:107], v7 offset:64
	ds_read_b128 v[108:111], v7 offset:80
	ds_read_b128 v[112:115], v7 offset:96
	ds_read_b128 v[180:183], v7 offset:112
	ds_read_b128 v[26:29], v8 offset:0
	ds_read_b128 v[30:33], v8 offset:16
	ds_read_b128 v[34:37], v8 offset:32
	ds_read_b128 v[38:41], v8 offset:48
	ds_read_b128 v[42:45], v8 offset:64
	ds_read_b128 v[46:49], v8 offset:80
	ds_read_b128 v[50:53], v8 offset:96
	ds_read_b128 v[54:57], v8 offset:112
	s_waitcnt lgkmcnt(0)
	v_lshl_add_u32 v68, v26, 10, v4
	v_lshl_add_u32 v69, v28, 10, v4
	v_lshl_add_u32 v70, v30, 10, v4
	v_lshl_add_u32 v71, v32, 10, v4
	v_lshl_add_u32 v72, v34, 10, v4
	v_lshl_add_u32 v73, v36, 10, v4
	v_lshl_add_u32 v74, v38, 10, v4
	v_lshl_add_u32 v75, v40, 10, v4
	v_lshl_add_u32 v76, v42, 10, v4
	v_lshl_add_u32 v77, v44, 10, v4
	v_lshl_add_u32 v78, v46, 10, v4
	v_lshl_add_u32 v79, v48, 10, v4
	v_lshl_add_u32 v80, v50, 10, v4
	v_lshl_add_u32 v81, v52, 10, v4
	v_lshl_add_u32 v82, v54, 10, v4
	v_lshl_add_u32 v83, v56, 10, v4
	s_waitcnt vmcnt(16)
	v_cvt_pk_f32_fp8_e32 v[26:27], v120
	v_cvt_pk_f32_fp8_sdwa v[28:29], v120 src0_sel:WORD_1
	v_cvt_pk_f32_fp8_e32 v[30:31], v121
	v_cvt_pk_f32_fp8_sdwa v[32:33], v121 src0_sel:WORD_1
	v_cvt_pk_f32_fp8_e32 v[34:35], v122
	v_cvt_pk_f32_fp8_sdwa v[36:37], v122 src0_sel:WORD_1
	v_cvt_pk_f32_fp8_e32 v[38:39], v123
	v_cvt_pk_f32_fp8_sdwa v[40:41], v123 src0_sel:WORD_1
	v_cvt_pk_f32_fp8_e32 v[42:43], v124
	v_cvt_pk_f32_fp8_sdwa v[44:45], v124 src0_sel:WORD_1
	v_cvt_pk_f32_fp8_e32 v[46:47], v125
	v_cvt_pk_f32_fp8_sdwa v[48:49], v125 src0_sel:WORD_1
	v_cvt_pk_f32_fp8_e32 v[50:51], v126
	v_cvt_pk_f32_fp8_sdwa v[52:53], v126 src0_sel:WORD_1
	v_cvt_pk_f32_fp8_e32 v[54:55], v127
	v_cvt_pk_f32_fp8_sdwa v[56:57], v127 src0_sel:WORD_1
	global_load_dwordx4 v[120:123], v68, s[12:13]
	global_load_dwordx4 v[124:127], v69, s[12:13]
	v_pk_mul_f32 v[10:11], v[84:85], v[26:27] op_sel:[1,0]
	v_pk_mul_f32 v[12:13], v[84:85], v[28:29] op_sel:[1,0]
	v_pk_mul_f32 v[14:15], v[84:85], v[30:31] op_sel:[1,0]
	v_pk_mul_f32 v[16:17], v[84:85], v[32:33] op_sel:[1,0]
	v_pk_mul_f32 v[18:19], v[84:85], v[34:35] op_sel:[1,0]
	v_pk_mul_f32 v[20:21], v[84:85], v[36:37] op_sel:[1,0]
	v_pk_mul_f32 v[22:23], v[84:85], v[38:39] op_sel:[1,0]
	v_pk_mul_f32 v[24:25], v[84:85], v[40:41] op_sel:[1,0]
	v_pk_fma_f32 v[10:11], v[86:87], v[42:43], v[10:11] op_sel:[1,0,0]
	v_pk_fma_f32 v[12:13], v[86:87], v[44:45], v[12:13] op_sel:[1,0,0]
	v_pk_fma_f32 v[14:15], v[86:87], v[46:47], v[14:15] op_sel:[1,0,0]
	v_pk_fma_f32 v[16:17], v[86:87], v[48:49], v[16:17] op_sel:[1,0,0]
	v_pk_fma_f32 v[18:19], v[86:87], v[50:51], v[18:19] op_sel:[1,0,0]
	v_pk_fma_f32 v[20:21], v[86:87], v[52:53], v[20:21] op_sel:[1,0,0]
	v_pk_fma_f32 v[22:23], v[86:87], v[54:55], v[22:23] op_sel:[1,0,0]
	v_pk_fma_f32 v[24:25], v[86:87], v[56:57], v[24:25] op_sel:[1,0,0]
	s_waitcnt vmcnt(16)
	v_cvt_pk_f32_fp8_e32 v[26:27], v128
	v_cvt_pk_f32_fp8_sdwa v[28:29], v128 src0_sel:WORD_1
	v_cvt_pk_f32_fp8_e32 v[30:31], v129
	v_cvt_pk_f32_fp8_sdwa v[32:33], v129 src0_sel:WORD_1
	v_cvt_pk_f32_fp8_e32 v[34:35], v130
	v_cvt_pk_f32_fp8_sdwa v[36:37], v130 src0_sel:WORD_1
	v_cvt_pk_f32_fp8_e32 v[38:39], v131
	v_cvt_pk_f32_fp8_sdwa v[40:41], v131 src0_sel:WORD_1
	v_cvt_pk_f32_fp8_e32 v[42:43], v132
	v_cvt_pk_f32_fp8_sdwa v[44:45], v132 src0_sel:WORD_1
	v_cvt_pk_f32_fp8_e32 v[46:47], v133
	v_cvt_pk_f32_fp8_sdwa v[48:49], v133 src0_sel:WORD_1
	v_cvt_pk_f32_fp8_e32 v[50:51], v134
	v_cvt_pk_f32_fp8_sdwa v[52:53], v134 src0_sel:WORD_1
	v_cvt_pk_f32_fp8_e32 v[54:55], v135
	v_cvt_pk_f32_fp8_sdwa v[56:57], v135 src0_sel:WORD_1
	global_load_dwordx4 v[128:131], v70, s[12:13]
	global_load_dwordx4 v[132:135], v71, s[12:13]
	v_pk_fma_f32 v[10:11], v[88:89], v[26:27], v[10:11] op_sel:[1,0,0]
	v_pk_fma_f32 v[12:13], v[88:89], v[28:29], v[12:13] op_sel:[1,0,0]
	v_pk_fma_f32 v[14:15], v[88:89], v[30:31], v[14:15] op_sel:[1,0,0]
	v_pk_fma_f32 v[16:17], v[88:89], v[32:33], v[16:17] op_sel:[1,0,0]
	v_pk_fma_f32 v[18:19], v[88:89], v[34:35], v[18:19] op_sel:[1,0,0]
	v_pk_fma_f32 v[20:21], v[88:89], v[36:37], v[20:21] op_sel:[1,0,0]
	v_pk_fma_f32 v[22:23], v[88:89], v[38:39], v[22:23] op_sel:[1,0,0]
	v_pk_fma_f32 v[24:25], v[88:89], v[40:41], v[24:25] op_sel:[1,0,0]
	v_pk_fma_f32 v[10:11], v[90:91], v[42:43], v[10:11] op_sel:[1,0,0]
	v_pk_fma_f32 v[12:13], v[90:91], v[44:45], v[12:13] op_sel:[1,0,0]
	v_pk_fma_f32 v[14:15], v[90:91], v[46:47], v[14:15] op_sel:[1,0,0]
	v_pk_fma_f32 v[16:17], v[90:91], v[48:49], v[16:17] op_sel:[1,0,0]
	v_pk_fma_f32 v[18:19], v[90:91], v[50:51], v[18:19] op_sel:[1,0,0]
	v_pk_fma_f32 v[20:21], v[90:91], v[52:53], v[20:21] op_sel:[1,0,0]
	v_pk_fma_f32 v[22:23], v[90:91], v[54:55], v[22:23] op_sel:[1,0,0]
	v_pk_fma_f32 v[24:25], v[90:91], v[56:57], v[24:25] op_sel:[1,0,0]
	s_waitcnt vmcnt(16)
;     ...
;     for (int j0 = 0; j0 < NTL * 16; j0 += 16) {
;         u32x4_t w[16]; float cj[16];
; #pragma unroll
;         for (int jj = 0; jj < 16; ++jj) { const u32x2_t pr = pl[j0 + jj]; const int ej = __builtin_amdgcn_readfirstlane((int)pr.x); cj[jj] = __uint_as_float(pr.y);
;             w[jj] = *(const u32x4_t*)(v8 + (size_t)ej * D + 16 * lane); }
; #pragma unroll
;         for (int jj = 0; jj < 16; ++jj) { const float c = cj[jj];
; #pragma unroll
;             for (int q = 0; q < 4; ++q) { const f32x2_t lo = __builtin_amdgcn_cvt_pk_f32_fp8((int)w[jj][q], false), hi = __builtin_amdgcn_cvt_pk_f32_fp8((int)w[jj][q], true);
;                 o[4 * q] += c * lo[0]; o[4 * q + 1] += c * lo[1]; o[4 * q + 2] += c * hi[0]; o[4 * q + 3] += c * hi[1]; } }
	v_cvt_pk_f32_fp8_e32 v[26:27], v136
	v_cvt_pk_f32_fp8_sdwa v[28:29], v136 src0_sel:WORD_1
	v_cvt_pk_f32_fp8_e32 v[30:31], v137
	v_cvt_pk_f32_fp8_sdwa v[32:33], v137 src0_sel:WORD_1
	v_cvt_pk_f32_fp8_e32 v[34:35], v138
	v_cvt_pk_f32_fp8_sdwa v[36:37], v138 src0_sel:WORD_1
	v_cvt_pk_f32_fp8_e32 v[38:39], v139
	v_cvt_pk_f32_fp8_sdwa v[40:41], v139 src0_sel:WORD_1
	v_cvt_pk_f32_fp8_e32 v[42:43], v140
	v_cvt_pk_f32_fp8_sdwa v[44:45], v140 src0_sel:WORD_1
	v_cvt_pk_f32_fp8_e32 v[46:47], v141
	v_cvt_pk_f32_fp8_sdwa v[48:49], v141 src0_sel:WORD_1
	v_cvt_pk_f32_fp8_e32 v[50:51], v142
	v_cvt_pk_f32_fp8_sdwa v[52:53], v142 src0_sel:WORD_1
	v_cvt_pk_f32_fp8_e32 v[54:55], v143
	v_cvt_pk_f32_fp8_sdwa v[56:57], v143 src0_sel:WORD_1
	global_load_dwordx4 v[136:139], v72, s[12:13]
	global_load_dwordx4 v[140:143], v73, s[12:13]
	v_pk_fma_f32 v[10:11], v[92:93], v[26:27], v[10:11] op_sel:[1,0,0]
	v_pk_fma_f32 v[12:13], v[92:93], v[28:29], v[12:13] op_sel:[1,0,0]
	v_pk_fma_f32 v[14:15], v[92:93], v[30:31], v[14:15] op_sel:[1,0,0]
	v_pk_fma_f32 v[16:17], v[92:93], v[32:33], v[16:17] op_sel:[1,0,0]
	v_pk_fma_f32 v[18:19], v[92:93], v[34:35], v[18:19] op_sel:[1,0,0]
	v_pk_fma_f32 v[20:21], v[92:93], v[36:37], v[20:21] op_sel:[1,0,0]
	v_pk_fma_f32 v[22:23], v[92:93], v[38:39], v[22:23] op_sel:[1,0,0]
	v_pk_fma_f32 v[24:25], v[92:93], v[40:41], v[24:25] op_sel:[1,0,0]
	v_pk_fma_f32 v[10:11], v[94:95], v[42:43], v[10:11] op_sel:[1,0,0]
	v_pk_fma_f32 v[12:13], v[94:95], v[44:45], v[12:13] op_sel:[1,0,0]
	v_pk_fma_f32 v[14:15], v[94:95], v[46:47], v[14:15] op_sel:[1,0,0]
	v_pk_fma_f32 v[16:17], v[94:95], v[48:49], v[16:17] op_sel:[1,0,0]
	v_pk_fma_f32 v[18:19], v[94:95], v[50:51], v[18:19] op_sel:[1,0,0]
	v_pk_fma_f32 v[20:21], v[94:95], v[52:53], v[20:21] op_sel:[1,0,0]
	v_pk_fma_f32 v[22:23], v[94:95], v[54:55], v[22:23] op_sel:[1,0,0]
	v_pk_fma_f32 v[24:25], v[94:95], v[56:57], v[24:25] op_sel:[1,0,0]
	s_waitcnt vmcnt(16)
	v_cvt_pk_f32_fp8_e32 v[26:27], v144
	v_cvt_pk_f32_fp8_sdwa v[28:29], v144 src0_sel:WORD_1
	v_cvt_pk_f32_fp8_e32 v[30:31], v145
	v_cvt_pk_f32_fp8_sdwa v[32:33], v145 src0_sel:WORD_1
	v_cvt_pk_f32_fp8_e32 v[34:35], v146
	v_cvt_pk_f32_fp8_sdwa v[36:37], v146 src0_sel:WORD_1
	v_cvt_pk_f32_fp8_e32 v[38:39], v147
	v_cvt_pk_f32_fp8_sdwa v[40:41], v147 src0_sel:WORD_1
	v_cvt_pk_f32_fp8_e32 v[42:43], v148
	v_cvt_pk_f32_fp8_sdwa v[44:45], v148 src0_sel:WORD_1
	v_cvt_pk_f32_fp8_e32 v[46:47], v149
	v_cvt_pk_f32_fp8_sdwa v[48:49], v149 src0_sel:WORD_1
	v_cvt_pk_f32_fp8_e32 v[50:51], v150
	v_cvt_pk_f32_fp8_sdwa v[52:53], v150 src0_sel:WORD_1
	v_cvt_pk_f32_fp8_e32 v[54:55], v151
	v_cvt_pk_f32_fp8_sdwa v[56:57], v151 src0_sel:WORD_1
	global_load_dwordx4 v[144:147], v74, s[12:13]
	global_load_dwordx4 v[148:151], v75, s[12:13]
	v_pk_fma_f32 v[10:11], v[96:97], v[26:27], v[10:11] op_sel:[1,0,0]
	v_pk_fma_f32 v[12:13], v[96:97], v[28:29], v[12:13] op_sel:[1,0,0]
	v_pk_fma_f32 v[14:15], v[96:97], v[30:31], v[14:15] op_sel:[1,0,0]
	v_pk_fma_f32 v[16:17], v[96:97], v[32:33], v[16:17] op_sel:[1,0,0]
	v_pk_fma_f32 v[18:19], v[96:97], v[34:35], v[18:19] op_sel:[1,0,0]
	v_pk_fma_f32 v[20:21], v[96:97], v[36:37], v[20:21] op_sel:[1,0,0]
	v_pk_fma_f32 v[22:23], v[96:97], v[38:39], v[22:23] op_sel:[1,0,0]
	v_pk_fma_f32 v[24:25], v[96:97], v[40:41], v[24:25] op_sel:[1,0,0]
	v_pk_fma_f32 v[10:11], v[98:99], v[42:43], v[10:11] op_sel:[1,0,0]
	v_pk_fma_f32 v[12:13], v[98:99], v[44:45], v[12:13] op_sel:[1,0,0]
	v_pk_fma_f32 v[14:15], v[98:99], v[46:47], v[14:15] op_sel:[1,0,0]
	v_pk_fma_f32 v[16:17], v[98:99], v[48:49], v[16:17] op_sel:[1,0,0]
	v_pk_fma_f32 v[18:19], v[98:99], v[50:51], v[18:19] op_sel:[1,0,0]
	v_pk_fma_f32 v[20:21], v[98:99], v[52:53], v[20:21] op_sel:[1,0,0]
	v_pk_fma_f32 v[22:23], v[98:99], v[54:55], v[22:23] op_sel:[1,0,0]
	v_pk_fma_f32 v[24:25], v[98:99], v[56:57], v[24:25] op_sel:[1,0,0]
	s_waitcnt vmcnt(16)
	v_cvt_pk_f32_fp8_e32 v[26:27], v152
	v_cvt_pk_f32_fp8_sdwa v[28:29], v152 src0_sel:WORD_1
	v_cvt_pk_f32_fp8_e32 v[30:31], v153
	v_cvt_pk_f32_fp8_sdwa v[32:33], v153 src0_sel:WORD_1
	v_cvt_pk_f32_fp8_e32 v[34:35], v154
	v_cvt_pk_f32_fp8_sdwa v[36:37], v154 src0_sel:WORD_1
	v_cvt_pk_f32_fp8_e32 v[38:39], v155
	v_cvt_pk_f32_fp8_sdwa v[40:41], v155 src0_sel:WORD_1
	v_cvt_pk_f32_fp8_e32 v[42:43], v156
	v_cvt_pk_f32_fp8_sdwa v[44:45], v156 src0_sel:WORD_1
	v_cvt_pk_f32_fp8_e32 v[46:47], v157
	v_cvt_pk_f32_fp8_sdwa v[48:49], v157 src0_sel:WORD_1
	v_cvt_pk_f32_fp8_e32 v[50:51], v158
	v_cvt_pk_f32_fp8_sdwa v[52:53], v158 src0_sel:WORD_1
	v_cvt_pk_f32_fp8_e32 v[54:55], v159
	v_cvt_pk_f32_fp8_sdwa v[56:57], v159 src0_sel:WORD_1
	global_load_dwordx4 v[152:155], v76, s[12:13]
	global_load_dwordx4 v[156:159], v77, s[12:13]
	v_pk_fma_f32 v[10:11], v[104:105], v[26:27], v[10:11] op_sel:[1,0,0]
	v_pk_fma_f32 v[12:13], v[104:105], v[28:29], v[12:13] op_sel:[1,0,0]
	v_pk_fma_f32 v[14:15], v[104:105], v[30:31], v[14:15] op_sel:[1,0,0]
	v_pk_fma_f32 v[16:17], v[104:105], v[32:33], v[16:17] op_sel:[1,0,0]
	v_pk_fma_f32 v[18:19], v[104:105], v[34:35], v[18:19] op_sel:[1,0,0]
	v_pk_fma_f32 v[20:21], v[104:105], v[36:37], v[20:21] op_sel:[1,0,0]
	v_pk_fma_f32 v[22:23], v[104:105], v[38:39], v[22:23] op_sel:[1,0,0]
	v_pk_fma_f32 v[24:25], v[104:105], v[40:41], v[24:25] op_sel:[1,0,0]
	v_pk_fma_f32 v[10:11], v[106:107], v[42:43], v[10:11] op_sel:[1,0,0]
	v_pk_fma_f32 v[12:13], v[106:107], v[44:45], v[12:13] op_sel:[1,0,0]
	v_pk_fma_f32 v[14:15], v[106:107], v[46:47], v[14:15] op_sel:[1,0,0]
	v_pk_fma_f32 v[16:17], v[106:107], v[48:49], v[16:17] op_sel:[1,0,0]
	v_pk_fma_f32 v[18:19], v[106:107], v[50:51], v[18:19] op_sel:[1,0,0]
	v_pk_fma_f32 v[20:21], v[106:107], v[52:53], v[20:21] op_sel:[1,0,0]
	v_pk_fma_f32 v[22:23], v[106:107], v[54:55], v[22:23] op_sel:[1,0,0]
	v_pk_fma_f32 v[24:25], v[106:107], v[56:57], v[24:25] op_sel:[1,0,0]
	s_waitcnt vmcnt(16)
;     ...
;     for (int j0 = 0; j0 < NTL * 16; j0 += 16) {
;         u32x4_t w[16]; float cj[16];
; #pragma unroll
;         for (int jj = 0; jj < 16; ++jj) { const u32x2_t pr = pl[j0 + jj]; const int ej = __builtin_amdgcn_readfirstlane((int)pr.x); cj[jj] = __uint_as_float(pr.y);
;             w[jj] = *(const u32x4_t*)(v8 + (size_t)ej * D + 16 * lane); }
; #pragma unroll
;         for (int jj = 0; jj < 16; ++jj) { const float c = cj[jj];
; #pragma unroll
;             for (int q = 0; q < 4; ++q) { const f32x2_t lo = __builtin_amdgcn_cvt_pk_f32_fp8((int)w[jj][q], false), hi = __builtin_amdgcn_cvt_pk_f32_fp8((int)w[jj][q], true);
;                 o[4 * q] += c * lo[0]; o[4 * q + 1] += c * lo[1]; o[4 * q + 2] += c * hi[0]; o[4 * q + 3] += c * hi[1]; } }
	v_cvt_pk_f32_fp8_e32 v[26:27], v160
	v_cvt_pk_f32_fp8_sdwa v[28:29], v160 src0_sel:WORD_1
	v_cvt_pk_f32_fp8_e32 v[30:31], v161
	v_cvt_pk_f32_fp8_sdwa v[32:33], v161 src0_sel:WORD_1
	v_cvt_pk_f32_fp8_e32 v[34:35], v162
	v_cvt_pk_f32_fp8_sdwa v[36:37], v162 src0_sel:WORD_1
	v_cvt_pk_f32_fp8_e32 v[38:39], v163
	v_cvt_pk_f32_fp8_sdwa v[40:41], v163 src0_sel:WORD_1
	v_cvt_pk_f32_fp8_e32 v[42:43], v164
	v_cvt_pk_f32_fp8_sdwa v[44:45], v164 src0_sel:WORD_1
	v_cvt_pk_f32_fp8_e32 v[46:47], v165
	v_cvt_pk_f32_fp8_sdwa v[48:49], v165 src0_sel:WORD_1
	v_cvt_pk_f32_fp8_e32 v[50:51], v166
	v_cvt_pk_f32_fp8_sdwa v[52:53], v166 src0_sel:WORD_1
	v_cvt_pk_f32_fp8_e32 v[54:55], v167
	v_cvt_pk_f32_fp8_sdwa v[56:57], v167 src0_sel:WORD_1
	global_load_dwordx4 v[160:163], v78, s[12:13]
	global_load_dwordx4 v[164:167], v79, s[12:13]
	v_pk_fma_f32 v[10:11], v[108:109], v[26:27], v[10:11] op_sel:[1,0,0]
	v_pk_fma_f32 v[12:13], v[108:109], v[28:29], v[12:13] op_sel:[1,0,0]
	v_pk_fma_f32 v[14:15], v[108:109], v[30:31], v[14:15] op_sel:[1,0,0]
	v_pk_fma_f32 v[16:17], v[108:109], v[32:33], v[16:17] op_sel:[1,0,0]
	v_pk_fma_f32 v[18:19], v[108:109], v[34:35], v[18:19] op_sel:[1,0,0]
	v_pk_fma_f32 v[20:21], v[108:109], v[36:37], v[20:21] op_sel:[1,0,0]
	v_pk_fma_f32 v[22:23], v[108:109], v[38:39], v[22:23] op_sel:[1,0,0]
	v_pk_fma_f32 v[24:25], v[108:109], v[40:41], v[24:25] op_sel:[1,0,0]
	v_pk_fma_f32 v[10:11], v[110:111], v[42:43], v[10:11] op_sel:[1,0,0]
	v_pk_fma_f32 v[12:13], v[110:111], v[44:45], v[12:13] op_sel:[1,0,0]
	v_pk_fma_f32 v[14:15], v[110:111], v[46:47], v[14:15] op_sel:[1,0,0]
	v_pk_fma_f32 v[16:17], v[110:111], v[48:49], v[16:17] op_sel:[1,0,0]
	v_pk_fma_f32 v[18:19], v[110:111], v[50:51], v[18:19] op_sel:[1,0,0]
	v_pk_fma_f32 v[20:21], v[110:111], v[52:53], v[20:21] op_sel:[1,0,0]
	v_pk_fma_f32 v[22:23], v[110:111], v[54:55], v[22:23] op_sel:[1,0,0]
	v_pk_fma_f32 v[24:25], v[110:111], v[56:57], v[24:25] op_sel:[1,0,0]
	s_waitcnt vmcnt(16)
	v_cvt_pk_f32_fp8_e32 v[26:27], v168
	v_cvt_pk_f32_fp8_sdwa v[28:29], v168 src0_sel:WORD_1
	v_cvt_pk_f32_fp8_e32 v[30:31], v169
	v_cvt_pk_f32_fp8_sdwa v[32:33], v169 src0_sel:WORD_1
	v_cvt_pk_f32_fp8_e32 v[34:35], v170
	v_cvt_pk_f32_fp8_sdwa v[36:37], v170 src0_sel:WORD_1
	v_cvt_pk_f32_fp8_e32 v[38:39], v171
	v_cvt_pk_f32_fp8_sdwa v[40:41], v171 src0_sel:WORD_1
	v_cvt_pk_f32_fp8_e32 v[42:43], v172
	v_cvt_pk_f32_fp8_sdwa v[44:45], v172 src0_sel:WORD_1
	v_cvt_pk_f32_fp8_e32 v[46:47], v173
	v_cvt_pk_f32_fp8_sdwa v[48:49], v173 src0_sel:WORD_1
	v_cvt_pk_f32_fp8_e32 v[50:51], v174
	v_cvt_pk_f32_fp8_sdwa v[52:53], v174 src0_sel:WORD_1
	v_cvt_pk_f32_fp8_e32 v[54:55], v175
	v_cvt_pk_f32_fp8_sdwa v[56:57], v175 src0_sel:WORD_1
	global_load_dwordx4 v[168:171], v80, s[12:13]
	global_load_dwordx4 v[172:175], v81, s[12:13]
	v_pk_fma_f32 v[10:11], v[112:113], v[26:27], v[10:11] op_sel:[1,0,0]
	v_pk_fma_f32 v[12:13], v[112:113], v[28:29], v[12:13] op_sel:[1,0,0]
	v_pk_fma_f32 v[14:15], v[112:113], v[30:31], v[14:15] op_sel:[1,0,0]
	v_pk_fma_f32 v[16:17], v[112:113], v[32:33], v[16:17] op_sel:[1,0,0]
	v_pk_fma_f32 v[18:19], v[112:113], v[34:35], v[18:19] op_sel:[1,0,0]
	v_pk_fma_f32 v[20:21], v[112:113], v[36:37], v[20:21] op_sel:[1,0,0]
	v_pk_fma_f32 v[22:23], v[112:113], v[38:39], v[22:23] op_sel:[1,0,0]
	v_pk_fma_f32 v[24:25], v[112:113], v[40:41], v[24:25] op_sel:[1,0,0]
	v_pk_fma_f32 v[10:11], v[114:115], v[42:43], v[10:11] op_sel:[1,0,0]
	v_pk_fma_f32 v[12:13], v[114:115], v[44:45], v[12:13] op_sel:[1,0,0]
	v_pk_fma_f32 v[14:15], v[114:115], v[46:47], v[14:15] op_sel:[1,0,0]
	v_pk_fma_f32 v[16:17], v[114:115], v[48:49], v[16:17] op_sel:[1,0,0]
	v_pk_fma_f32 v[18:19], v[114:115], v[50:51], v[18:19] op_sel:[1,0,0]
	v_pk_fma_f32 v[20:21], v[114:115], v[52:53], v[20:21] op_sel:[1,0,0]
	v_pk_fma_f32 v[22:23], v[114:115], v[54:55], v[22:23] op_sel:[1,0,0]
	v_pk_fma_f32 v[24:25], v[114:115], v[56:57], v[24:25] op_sel:[1,0,0]
	s_waitcnt vmcnt(16)
; #define LAS __attribute__((address_space(3)))
;     ...
;     for (int j0 = 0; j0 < NTL * 16; j0 += 16) {
;         u32x4_t w[16]; float cj[16];
; #pragma unroll
;         for (int jj = 0; jj < 16; ++jj) { const u32x2_t pr = pl[j0 + jj]; const int ej = __builtin_amdgcn_readfirstlane((int)pr.x); cj[jj] = __uint_as_float(pr.y);
;             w[jj] = *(const u32x4_t*)(v8 + (size_t)ej * D + 16 * lane); }
; #pragma unroll
;         for (int jj = 0; jj < 16; ++jj) { const float c = cj[jj];
; #pragma unroll
;             for (int q = 0; q < 4; ++q) { const f32x2_t lo = __builtin_amdgcn_cvt_pk_f32_fp8((int)w[jj][q], false), hi = __builtin_amdgcn_cvt_pk_f32_fp8((int)w[jj][q], true);
;                 o[4 * q] += c * lo[0]; o[4 * q + 1] += c * lo[1]; o[4 * q + 2] += c * hi[0]; o[4 * q + 3] += c * hi[1]; } }
;     }
;     if (NTL < 8) {
;         if (half == 1) {
; #pragma unroll
;             for (int q = 0; q < 4; ++q) *(LAS f32x4_t*)(xch + lane * 16 + 4 * q) = (f32x4_t){o[4 * q], o[4 * q + 1], o[4 * q + 2], o[4 * q + 3]};
;         }
;         __syncthreads();
;         if (half == 1) return;
; #pragma unroll
;         for (int q = 0; q < 4; ++q) { const f32x4_t t4 = *(const LAS f32x4_t*)(xch + lane * 16 + 4 * q); o[4 * q] += t4[0]; o[4 * q + 1] += t4[1]; o[4 * q + 2] += t4[2]; o[4 * q + 3] += t4[3]; }
;     }
;     const float* gp = gate2 + (size_t)row_seq(r) * 6144 + 16 * lane;
;     float* xp = x + (size_t)r * D + 16 * lane;
; #pragma unroll
;     for (int q = 0; q < 4; ++q) {
;         float4 xa = *(const float4*)(xp + 4 * q); const float4 ga = *(const float4*)(gp + 4 * q);
;         xa.x += ga.x * o[4 * q]; xa.y += ga.y * o[4 * q + 1]; xa.z += ga.z * o[4 * q + 2]; xa.w += ga.w * o[4 * q + 3];
;         *(float4*)(xp + 4 * q) = xa;
;         o[4 * q] = xa.x; o[4 * q + 1] = xa.y; o[4 * q + 2] = xa.z; o[4 * q + 3] = xa.w;
;     }
	v_cvt_pk_f32_fp8_e32 v[26:27], v188
	v_cvt_pk_f32_fp8_sdwa v[28:29], v188 src0_sel:WORD_1
	v_cvt_pk_f32_fp8_e32 v[30:31], v189
	v_cvt_pk_f32_fp8_sdwa v[32:33], v189 src0_sel:WORD_1
	v_cvt_pk_f32_fp8_e32 v[34:35], v190
	v_cvt_pk_f32_fp8_sdwa v[36:37], v190 src0_sel:WORD_1
	v_cvt_pk_f32_fp8_e32 v[38:39], v191
	v_cvt_pk_f32_fp8_sdwa v[40:41], v191 src0_sel:WORD_1
	v_cvt_pk_f32_fp8_e32 v[42:43], v192
	v_cvt_pk_f32_fp8_sdwa v[44:45], v192 src0_sel:WORD_1
	v_cvt_pk_f32_fp8_e32 v[46:47], v193
	v_cvt_pk_f32_fp8_sdwa v[48:49], v193 src0_sel:WORD_1
	v_cvt_pk_f32_fp8_e32 v[50:51], v194
	v_cvt_pk_f32_fp8_sdwa v[52:53], v194 src0_sel:WORD_1
	v_cvt_pk_f32_fp8_e32 v[54:55], v195
	v_cvt_pk_f32_fp8_sdwa v[56:57], v195 src0_sel:WORD_1
	global_load_dwordx4 v[188:191], v82, s[12:13]
	global_load_dwordx4 v[192:195], v83, s[12:13]
	v_pk_fma_f32 v[10:11], v[180:181], v[26:27], v[10:11] op_sel:[1,0,0]
	v_pk_fma_f32 v[12:13], v[180:181], v[28:29], v[12:13] op_sel:[1,0,0]
	v_pk_fma_f32 v[14:15], v[180:181], v[30:31], v[14:15] op_sel:[1,0,0]
	v_pk_fma_f32 v[16:17], v[180:181], v[32:33], v[16:17] op_sel:[1,0,0]
	v_pk_fma_f32 v[18:19], v[180:181], v[34:35], v[18:19] op_sel:[1,0,0]
	v_pk_fma_f32 v[20:21], v[180:181], v[36:37], v[20:21] op_sel:[1,0,0]
	v_pk_fma_f32 v[22:23], v[180:181], v[38:39], v[22:23] op_sel:[1,0,0]
	v_pk_fma_f32 v[24:25], v[180:181], v[40:41], v[24:25] op_sel:[1,0,0]
	v_pk_fma_f32 v[10:11], v[182:183], v[42:43], v[10:11] op_sel:[1,0,0]
	v_pk_fma_f32 v[12:13], v[182:183], v[44:45], v[12:13] op_sel:[1,0,0]
	v_pk_fma_f32 v[14:15], v[182:183], v[46:47], v[14:15] op_sel:[1,0,0]
	v_pk_fma_f32 v[16:17], v[182:183], v[48:49], v[16:17] op_sel:[1,0,0]
	v_pk_fma_f32 v[18:19], v[182:183], v[50:51], v[18:19] op_sel:[1,0,0]
	v_pk_fma_f32 v[20:21], v[182:183], v[52:53], v[20:21] op_sel:[1,0,0]
	v_pk_fma_f32 v[22:23], v[182:183], v[54:55], v[22:23] op_sel:[1,0,0]
	v_pk_fma_f32 v[24:25], v[182:183], v[56:57], v[24:25] op_sel:[1,0,0]
	s_nop 1
	v_permlane32_swap_b32_e32 v10, v18
	v_permlane32_swap_b32_e32 v11, v19
	v_permlane32_swap_b32_e32 v12, v20
	v_permlane32_swap_b32_e32 v13, v21
	v_permlane32_swap_b32_e32 v14, v22
	v_permlane32_swap_b32_e32 v15, v23
	v_permlane32_swap_b32_e32 v16, v24
	v_permlane32_swap_b32_e32 v17, v25
	v_add_f32_e32 v10, v10, v18
	v_add_f32_e32 v11, v11, v19
	v_add_f32_e32 v12, v12, v20
	v_add_f32_e32 v13, v13, v21
	v_add_f32_e32 v14, v14, v22
	v_add_f32_e32 v15, v15, v23
	v_add_f32_e32 v16, v16, v24
	v_add_f32_e32 v17, v17, v25
	s_nop 1
	v_permlane16_swap_b32_e32 v10, v14
	v_permlane16_swap_b32_e32 v11, v15
	v_permlane16_swap_b32_e32 v12, v16
	v_permlane16_swap_b32_e32 v13, v17
	v_add_f32_e32 v10, v10, v14
	v_add_f32_e32 v11, v11, v15
	v_add_f32_e32 v12, v12, v16
	v_add_f32_e32 v13, v13, v17
	v_cndmask_b32_e64 v14, v10, v12, s[24:25]
	v_cndmask_b32_e64 v16, v12, v10, s[24:25]
	v_cndmask_b32_e64 v15, v11, v13, s[24:25]
	v_cndmask_b32_e64 v17, v13, v11, s[24:25]
	s_nop 1
	v_add_f32_dpp v62, v16, v14 row_ror:8 row_mask:0xf bank_mask:0xf
	v_add_f32_dpp v63, v17, v15 row_ror:8 row_mask:0xf bank_mask:0xf
	s_waitcnt vmcnt(16)
	v_pk_fma_f32 v[58:59], v[62:63], v[60:61], v[58:59]
	global_store_dwordx2 v6, v[58:59], s[14:15]
	s_add_u32 s22, s22, 1
	s_cmp_lg_u32 s22, 64
	s_cbranch_scc1 .Lg2_loop
	s_waitcnt vmcnt(0)
	v_cmp_gt_u32_e32 vcc, 8, v116
	s_nop 1
	s_ashr_i32 s9, s8, 31
	s_lshl_b64 s[18:19], s[8:9], 24
	s_lshl_b64 s[10:11], s[8:9], 16
	s_add_u32 s9, s6, s10
	s_addc_u32 s13, s7, s11
	s_add_u32 s10, s9, 0x2fa42100
	s_addc_u32 s11, s13, 0
	s_add_u32 s12, s9, 0x2fa82100
	s_addc_u32 s13, s13, 0
	s_add_u32 s14, s6, 0x1b292100
	s_addc_u32 s15, s7, 0
	s_add_u32 s16, s6, 0x1bb12100
	s_addc_u32 s17, s7, 0
	s_add_u32 s18, s6, s18
	s_addc_u32 s19, s7, s19
	v_lshl_add_u64 v[2:3], s[18:19], 0, v[102:103]
	s_mov_b64 s[20:21], 0x1fa42100
	v_lshl_add_u64 v[104:105], v[2:3], 0, s[20:21]
	v_mov_b32_e32 v2, 0x1100000
	v_cndmask_b32_e64 v66, v2, 0, vcc
	v_lshl_add_u64 v[2:3], s[6:7], 0, v[66:67]
	s_add_u32 s49, s6, 0x4000
	v_lshl_add_u64 v[2:3], v[2:3], 0, v[102:103]
	s_mov_b64 s[20:21], 0x2fac2100
	s_addc_u32 s50, s7, 0
	v_lshl_add_u64 v[106:107], v[2:3], 0, s[20:21]
	s_add_u32 s20, s49, s47
	v_lshl_add_u64 v[2:3], s[18:19], 0, v[100:101]
	s_mov_b64 s[18:19], 0x27a42100
	s_addc_u32 s21, s50, s46
	v_lshl_add_u64 v[108:109], v[2:3], 0, s[18:19]
	v_lshlrev_b64 v[2:3], 2, v[100:101]
	v_lshl_add_u64 v[4:5], s[20:21], 0, v[2:3]
	s_mov_b64 s[18:19], 0x5000
	s_cmp_lt_i32 s8, 3
	v_lshl_add_u64 v[110:111], v[4:5], 0, s[18:19]
	s_cselect_b64 s[18:19], -1, 0
	s_add_i32 s24, s8, 1
	s_ashr_i32 s25, s24, 31
	s_lshl_b64 s[20:21], s[24:25], 12
	s_add_u32 s55, s6, 0x20e100
	s_addc_u32 s56, s7, 0
	s_lshl_b32 s26, s24, 2
	s_ashr_i32 s27, s26, 31
	s_mul_i32 s23, s24, 0xc000
	s_mul_hi_i32 s22, s24, 0xc000
	s_add_u32 s23, s6, s23
	s_addc_u32 s28, s7, s22
	s_add_u32 s22, s23, 0x1f812100
	s_addc_u32 s23, s28, 0
	s_add_u32 s57, s6, 0xcb8a100
	s_addc_u32 s58, s7, 0
	s_lshl_b64 s[28:29], s[24:25], 18
	s_add_u32 s59, s4, s28
	s_addc_u32 s60, s5, s29
	s_lshl_b32 s28, s24, 3
	s_ashr_i32 s29, s28, 31
	s_add_u32 s61, s6, 0xacda100
	s_mov_b32 s9, 0
	v_lshl_add_u64 v[112:113], s[4:5], 0, v[2:3]
	s_mul_hi_i32 s51, s24, 18
	s_mul_i32 s54, s24, 18
	s_addc_u32 s62, s7, 0
	s_lshl_b64 s[24:25], s[26:27], 2
	s_lshl_b64 s[26:27], s[28:29], 2
	s_mov_b32 s63, s48
	s_branch .LBB0_1087

;     DEVI float* rstd() const { return (float*)(ws + WS_RSTD); }
; DEVI cfp_t inp(int i) { const __attribute__((address_space(4))) cfp_t* k = (const __attribute__((address_space(4))) cfp_t*)__builtin_amdgcn_kernarg_segment_ptr(); typedef const __attribute__((address_space(1))) float* gcfp_t; const gcfp_t r = *(const volatile __attribute__((address_space(4))) gcfp_t*)(k + i); return (cfp_t)r; }
; DEVI void adaln_apply_1(const P& p, int l, int r, int lane, float (&v)[16]) { adaln_apply<1>(p, l, r, lane, v); }
;     ...
;     const float* gp = gate2 + (size_t)row_seq(r) * 6144 + 16 * lane;
;     float* xp = x + (size_t)r * D + 16 * lane;
; #pragma unroll
;     for (int q = 0; q < 4; ++q) {
;         float4 xa = *(const float4*)(xp + 4 * q); const float4 ga = *(const float4*)(gp + 4 * q);
;         xa.x += ga.x * o[4 * q]; xa.y += ga.y * o[4 * q + 1]; xa.z += ga.z * o[4 * q + 2]; xa.w += ga.w * o[4 * q + 3];
;         *(float4*)(xp + 4 * q) = xa;
;         o[4 * q] = xa.x; o[4 * q + 1] = xa.y; o[4 * q + 2] = xa.z; o[4 * q + 3] = xa.w;
;     }
;     __builtin_amdgcn_sched_barrier(0);
;     if (l + 1 < DEPTH) adaln_apply_1(p, l + 1, r, lane, o);
; template <int WHICH> DEVI void adaln_apply(const P& p, int l, int r, int lane_in, float (&v)[16]) {
;     int lane = lane_in; asm volatile("" : "+v"(lane));
;     const float* g = inp(WHICH == 1 ? 9 : 10) + (size_t)l * D + 16 * lane;
;     const int osh = (WHICH == 1 ? 0 : 3) * D, osc = (WHICH == 1 ? 1 : 4) * D;
;     float ss = 0.f;
; #pragma unroll
;     for (int i = 0; i < 16; ++i) ss += v[i] * v[i];
;     const float rstd = rsqrtf(wave_sum(ss) * (1.f / D) + EPS);
.LBB0_1111:
	s_add_i32 s28, s64, s9
	s_mul_i32 s28, s28, s34
	s_add_i32 s28, s28, s48
	s_cmpk_gt_i32 s28, 0x3fff
	s_cbranch_scc1 .LBB0_1110
	v_mov_b32_e32 v114, 0
	s_mov_b32 s29, -16
	s_mov_b32 s30, s65
	v_mov_b32_e32 v115, v114
	v_mov_b32_e32 v120, v114
	v_mov_b32_e32 v121, v114
	v_mov_b32_e32 v118, v114
	v_mov_b32_e32 v119, v114
	v_mov_b32_e32 v128, v114
	v_mov_b32_e32 v129, v114
	v_mov_b32_e32 v130, v114
	v_mov_b32_e32 v131, v114
	v_mov_b32_e32 v122, v114
	v_mov_b32_e32 v123, v114
	v_mov_b32_e32 v124, v114
	v_mov_b32_e32 v125, v114
	v_mov_b32_e32 v126, v114
	v_mov_b32_e32 v127, v114
	s_ashr_i32 s29, s28, 31
	s_lshr_b32 s30, s29, 19
	s_add_i32 s30, s28, s30
	s_ashr_i32 s30, s30, 13
	v_mad_i64_i32 v[14:15], s[40:41], s30, v231, v[110:111]
	s_lshl_b64 s[40:41], s[28:29], 12
	s_nop 0
	v_lshl_add_u64 v[16:17], v[112:113], 0, s[40:41]
	global_load_dwordx4 v[2:5], v[14:15], off
	global_load_dwordx4 v[6:9], v[16:17], off sc1
	global_load_dwordx4 v[10:13], v[16:17], off offset:16 sc1
	s_waitcnt vmcnt(1)
	v_pk_fma_f32 v[30:31], v[120:121], v[2:3], v[6:7]
	v_pk_fma_f32 v[32:33], v[118:119], v[4:5], v[8:9]
	global_load_dwordx4 v[2:5], v[14:15], off offset:16
	s_waitcnt vmcnt(0)
	v_pk_fma_f32 v[22:23], v[128:129], v[2:3], v[10:11]
	v_pk_fma_f32 v[24:25], v[130:131], v[4:5], v[12:13]
	global_load_dwordx4 v[2:5], v[14:15], off offset:32
	global_load_dwordx4 v[6:9], v[16:17], off offset:32 sc1
	global_load_dwordx4 v[10:13], v[16:17], off offset:48 sc1
	s_waitcnt vmcnt(1)
	v_pk_fma_f32 v[26:27], v[122:123], v[2:3], v[6:7]
	v_pk_fma_f32 v[28:29], v[124:125], v[4:5], v[8:9]
	global_load_dwordx4 v[2:5], v[14:15], off offset:48
	s_waitcnt vmcnt(0)
	v_pk_fma_f32 v[18:19], v[126:127], v[2:3], v[10:11]
	v_pk_fma_f32 v[20:21], v[114:115], v[4:5], v[12:13]
	s_and_b64 vcc, exec, s[18:19]
	s_cbranch_vccz .LBB0_1110
	v_pk_mul_f32 v[2:3], v[30:31], v[30:31]
	v_pk_mul_f32 v[4:5], v[32:33], v[32:33]
	v_add_f32_e32 v2, v2, v3
	v_add_f32_e32 v2, v4, v2
	v_pk_mul_f32 v[6:7], v[22:23], v[22:23]
	v_add_f32_e32 v2, v5, v2
	v_add_f32_e32 v2, v2, v6
	v_pk_mul_f32 v[8:9], v[24:25], v[24:25]
	v_add_f32_e32 v2, v7, v2
	v_add_f32_e32 v2, v8, v2
	v_pk_mul_f32 v[10:11], v[26:27], v[26:27]
	v_add_f32_e32 v2, v9, v2
	v_add_f32_e32 v2, v2, v10
	v_pk_mul_f32 v[12:13], v[28:29], v[28:29]
	v_add_f32_e32 v2, v11, v2
	v_add_f32_e32 v2, v12, v2
	v_pk_mul_f32 v[14:15], v[18:19], v[18:19]
	v_add_f32_e32 v2, v13, v2
	v_add_f32_e32 v2, v2, v14
	v_pk_mul_f32 v[16:17], v[20:21], v[20:21]
	v_add_f32_e32 v2, v15, v2
	v_add_f32_e32 v2, v16, v2
	v_add_f32_e32 v4, v17, v2
	ds_bpermute_b32 v5, v179, v4
	v_mov_b32_e32 v58, v1
	s_load_dwordx2 s[40:41], s[0:1], 0x48
	s_ashr_i32 s31, s30, 31
	s_waitcnt lgkmcnt(0)
	v_add_f32_e32 v4, v4, v5
	ds_bpermute_b32 v5, v204, v4
	v_lshlrev_b32_e32 v60, 4, v58
	v_ashrrev_i32_e32 v61, 31, v60
	s_add_u32 s40, s40, s20
	s_addc_u32 s41, s41, s21
	s_waitcnt lgkmcnt(0)
	v_add_f32_e32 v4, v4, v5
	ds_bpermute_b32 v5, v205, v4
	v_lshlrev_b64 v[62:63], 2, v[60:61]
	v_lshl_add_u64 v[2:3], s[40:41], 0, v[62:63]
	s_mov_b32 s40, 0x800000
	s_add_u32 s30, s54, s30
	s_waitcnt lgkmcnt(0)
	v_add_f32_e32 v4, v4, v5
	ds_bpermute_b32 v5, v206, v4
	s_addc_u32 s31, s51, s31
	s_mulk_i32 s31, 0x6000
	s_mov_b64 s[42:43], 0x1000
	global_load_dwordx4 v[34:37], v[2:3], off offset:48
	global_load_dwordx4 v[38:41], v[2:3], off offset:32
	global_load_dwordx4 v[50:53], v[2:3], off offset:16
	global_load_dwordx4 v[68:71], v[2:3], off
	s_waitcnt lgkmcnt(0)
	v_add_f32_e32 v4, v4, v5
	ds_bpermute_b32 v5, v207, v4
	s_waitcnt lgkmcnt(0)
	v_add_f32_e32 v4, v4, v5
	ds_bpermute_b32 v5, v208, v4
	s_waitcnt lgkmcnt(0)
	v_add_f32_e32 v4, v4, v5
	v_fmamk_f32 v4, v4, 0x3a800000, v211
	v_cmp_gt_f32_e32 vcc, s40, v4
	v_mul_f32_e32 v5, 0x4b800000, v4
	s_mul_hi_u32 s40, s30, 0x6000
	v_cndmask_b32_e32 v4, v4, v5, vcc
	v_rsq_f32_e32 v4, v4
	s_add_i32 s40, s40, s31
	s_mulk_i32 s30, 0x6000
	s_add_u32 s30, s49, s30
	s_addc_u32 s31, s50, s40
	v_mul_f32_e32 v5, 0x45800000, v4
	v_lshl_add_u64 v[14:15], s[30:31], 0, v[62:63]
	s_movk_i32 s30, 0x1000
	v_cndmask_b32_e32 v59, v4, v5, vcc
	v_add_co_u32_e32 v2, vcc, s30, v14
	v_lshl_add_u64 v[4:5], v[14:15], 0, s[42:43]
	s_nop 0
	v_addc_co_u32_e32 v3, vcc, 0, v15, vcc
	global_load_dwordx4 v[72:75], v[2:3], off
	global_load_dwordx4 v[42:45], v[4:5], off offset:48
	global_load_dwordx4 v[46:49], v[4:5], off offset:32
	global_load_dwordx4 v[54:57], v[4:5], off offset:16
	s_nop 0
	global_load_dwordx4 v[2:5], v[14:15], off offset:48
	global_load_dwordx4 v[6:9], v[14:15], off offset:32
	global_load_dwordx4 v[10:13], v[14:15], off offset:16
	s_nop 0
	global_load_dwordx4 v[14:17], v[14:15], off
	v_mul_f32_e32 v30, v30, v59
	v_mul_f32_e32 v22, v22, v59
	s_lshl_b64 s[30:31], s[28:29], 11
	s_add_u32 s30, s55, s30
	s_addc_u32 s31, s56, s31
	s_waitcnt vmcnt(9)
	v_mul_f32_e32 v22, v22, v50
	s_waitcnt vmcnt(8)
	v_mul_f32_e32 v30, v68, v30
	s_waitcnt vmcnt(7)
	v_add_f32_e32 v64, 1.0, v72
	s_waitcnt vmcnt(0)
;     DEVI float* mod() const { return (float*)(ws + WS_MOD); }
;     DEVI float* rstd() const { return (float*)(ws + WS_RSTD); }
; template <int WHICH> DEVI void adaln_apply(const P& p, int l, int r, int lane_in, float (&v)[16]) {
;     ...
;     const float rstd = rsqrtf(wave_sum(ss) * (1.f / D) + EPS);
;     const float* md = p.mod() + ((size_t)l * NSEQ + row_seq(r)) * 6144 + 16 * lane;
; #pragma unroll
;     for (int q = 0; q < 4; ++q) {
;         const float4 gg = *(const float4*)(g + 4 * q), sc = *(const float4*)(md + osc + 4 * q), sh = *(const float4*)(md + osh + 4 * q);
;         v[4 * q] = v[4 * q] * rstd * gg.x * (1.f + sc.x) + sh.x; v[4 * q + 1] = v[4 * q + 1] * rstd * gg.y * (1.f + sc.y) + sh.y;
;         v[4 * q + 2] = v[4 * q + 2] * rstd * gg.z * (1.f + sc.z) + sh.z; v[4 * q + 3] = v[4 * q + 3] * rstd * gg.w * (1.f + sc.w) + sh.w;
;     }
;     u32x4_t* ob = (u32x4_t*)(p.hb() + (size_t)r * D + 16 * lane);
;     ob[0] = (u32x4_t){pk2bf(v[0], v[1]), pk2bf(v[2], v[3]), pk2bf(v[4], v[5]), pk2bf(v[6], v[7])};
;     ob[1] = (u32x4_t){pk2bf(v[8], v[9]), pk2bf(v[10], v[11]), pk2bf(v[12], v[13]), pk2bf(v[14], v[15])};
;     if constexpr (WHICH == 2) {
;         unsigned hi8[4], lo8[4];
; #pragma unroll
;         for (int q = 0; q < 4; ++q) { hi8[q] = pk4fp8(v[4 * q], v[4 * q + 1], v[4 * q + 2], v[4 * q + 3]);
;             const f32x2_t h01 = __builtin_amdgcn_cvt_pk_f32_fp8((int)hi8[q], false), h23 = __builtin_amdgcn_cvt_pk_f32_fp8((int)hi8[q], true);
;             lo8[q] = pk4fp8((v[4 * q] - h01[0]) * 32.f, (v[4 * q + 1] - h01[1]) * 32.f, (v[4 * q + 2] - h23[0]) * 32.f, (v[4 * q + 3] - h23[1]) * 32.f); }
;         *(u32x4_t*)(p.h8() + (size_t)r * D + 16 * lane) = (u32x4_t){hi8[0], hi8[1], hi8[2], hi8[3]};
;         *(u32x4_t*)(p.h8() + (size_t)M * D + (size_t)r * D + 16 * lane) = (u32x4_t){lo8[0], lo8[1], lo8[2], lo8[3]};
;     }
;     if constexpr (WHICH == 1) {
;         const float* dtb = inp(16) + l * 8; const float* fb = inp(22) + l * 4;
;         const float* ws = p.wsmall() + (size_t)l * 12 * D + 16 * lane;
;         float dot[12];
; #pragma unroll
;         for (int jj = 0; jj < 12; ++jj) { float a = 0.f;
; #pragma unroll
;             for (int q = 0; q < 4; ++q) { const float4 w = *(const float4*)(ws + (size_t)jj * D + 4 * q); a += v[4 * q] * w.x + v[4 * q + 1] * w.y + v[4 * q + 2] * w.z + v[4 * q + 3] * w.w; }
;             dot[jj] = wave_sum(a); }
	v_fma_f32 v14, v64, v30, v14
	v_mul_f32_e32 v30, v31, v59
	v_mul_f32_e32 v30, v69, v30
	v_add_f32_e32 v31, 1.0, v73
	v_fma_f32 v15, v31, v30, v15
	v_mul_f32_e32 v30, v32, v59
	v_mul_f32_e32 v30, v70, v30
	v_add_f32_e32 v31, 1.0, v74
	v_fma_f32 v16, v31, v30, v16
	v_mul_f32_e32 v30, v33, v59
	v_mul_f32_e32 v30, v71, v30
	v_add_f32_e32 v31, 1.0, v75
	v_fmac_f32_e32 v17, v31, v30
	v_add_f32_e32 v30, 1.0, v54
	v_fma_f32 v50, v22, v30, v10
	v_mul_f32_e32 v10, v23, v59
	v_mul_f32_e32 v10, v10, v51
	v_add_f32_e32 v22, 1.0, v55
	v_fma_f32 v51, v10, v22, v11
	v_mul_f32_e32 v10, v24, v59
	v_mul_f32_e32 v10, v10, v52
	v_add_f32_e32 v11, 1.0, v56
	v_fma_f32 v12, v10, v11, v12
	v_mul_f32_e32 v10, v25, v59
	v_mul_f32_e32 v10, v10, v53
	v_add_f32_e32 v11, 1.0, v57
	v_fmac_f32_e32 v13, v10, v11
	v_mul_f32_e32 v10, v26, v59
	v_mul_f32_e32 v10, v10, v38
	v_add_f32_e32 v11, 1.0, v46
	v_fma_f32 v38, v10, v11, v6
	v_mul_f32_e32 v6, v27, v59
	v_mul_f32_e32 v6, v6, v39
	v_add_f32_e32 v10, 1.0, v47
	v_fma_f32 v39, v6, v10, v7
	v_mul_f32_e32 v6, v28, v59
	v_mul_f32_e32 v6, v6, v40
	v_add_f32_e32 v7, 1.0, v48
	v_fma_f32 v40, v6, v7, v8
	v_mul_f32_e32 v6, v29, v59
	v_mul_f32_e32 v6, v6, v41
	v_add_f32_e32 v7, 1.0, v49
	v_fmac_f32_e32 v9, v6, v7
	v_mul_f32_e32 v6, v18, v59
	v_mul_f32_e32 v6, v6, v34
	v_add_f32_e32 v7, 1.0, v42
	v_fma_f32 v34, v6, v7, v2
	v_mul_f32_e32 v2, v19, v59
	v_mul_f32_e32 v2, v2, v35
	v_add_f32_e32 v6, 1.0, v43
	v_fma_f32 v35, v2, v6, v3
	v_mul_f32_e32 v2, v20, v59
	v_mul_f32_e32 v2, v2, v36
	v_add_f32_e32 v3, 1.0, v44
	v_fma_f32 v36, v2, v3, v4
	v_mul_f32_e32 v2, v21, v59
	v_mul_f32_e32 v2, v2, v37
	v_add_f32_e32 v3, 1.0, v45
	v_fmac_f32_e32 v5, v2, v3
	v_lshl_add_u64 v[2:3], v[60:61], 1, s[30:31]
	v_cvt_pk_bf16_f32 v18, v14, v15
	v_cvt_pk_bf16_f32 v19, v16, v17
	v_cvt_pk_bf16_f32 v20, v50, v51
	v_cvt_pk_bf16_f32 v21, v12, v13
	global_store_dwordx4 v[2:3], v[18:21], off
	s_nop 1
	v_cvt_pk_bf16_f32 v18, v38, v39
	v_cvt_pk_bf16_f32 v19, v40, v9
	v_cvt_pk_bf16_f32 v20, v34, v35
	v_cvt_pk_bf16_f32 v21, v36, v5
	global_store_dwordx4 v[2:3], v[18:21], off offset:16
	v_lshl_add_u64 v[2:3], s[22:23], 0, v[62:63]
	s_load_dwordx2 s[30:31], s[0:1], 0x80
	s_load_dwordx2 s[40:41], s[0:1], 0xb0
	global_load_dwordx4 v[18:21], v[2:3], off offset:48
	global_load_dwordx4 v[22:25], v[2:3], off offset:32
	global_load_dwordx4 v[26:29], v[2:3], off offset:16
	global_load_dwordx4 v[30:33], v[2:3], off
	s_waitcnt vmcnt(1)
	v_mul_f32_e32 v6, v51, v27
	s_waitcnt vmcnt(0)
	v_mul_f32_e32 v4, v15, v31
	v_fmac_f32_e32 v4, v14, v30
	v_fmac_f32_e32 v4, v16, v32
	v_fmac_f32_e32 v6, v50, v26
	v_fmac_f32_e32 v4, v17, v33
	v_fmac_f32_e32 v6, v12, v28
	v_add_f32_e32 v4, 0, v4
	v_fmac_f32_e32 v6, v13, v29
	v_add_f32_e32 v4, v4, v6
	v_mul_f32_e32 v6, v39, v23
	v_fmac_f32_e32 v6, v38, v22
	v_fmac_f32_e32 v6, v40, v24
	v_fmac_f32_e32 v6, v9, v25
	v_add_f32_e32 v4, v4, v6
	v_mul_f32_e32 v6, v35, v19
	v_fmac_f32_e32 v6, v34, v18
	v_fmac_f32_e32 v6, v36, v20
	v_fmac_f32_e32 v6, v5, v21
	v_add_f32_e32 v4, v4, v6
	ds_bpermute_b32 v6, v179, v4
	s_waitcnt lgkmcnt(0)
	v_add_f32_e32 v4, v4, v6
	ds_bpermute_b32 v6, v204, v4
	s_waitcnt lgkmcnt(0)
	v_add_f32_e32 v4, v4, v6
	ds_bpermute_b32 v6, v205, v4
	s_waitcnt lgkmcnt(0)
	v_add_f32_e32 v4, v4, v6
	ds_bpermute_b32 v6, v206, v4
	s_waitcnt lgkmcnt(0)
	v_add_f32_e32 v4, v4, v6
	ds_bpermute_b32 v6, v207, v4
	s_waitcnt lgkmcnt(0)
	v_add_f32_e32 v4, v4, v6
	v_lshl_add_u64 v[6:7], v[2:3], 0, s[42:43]
	s_movk_i32 s42, 0x2000
	v_add_co_u32_e32 v10, vcc, s42, v2
	s_mov_b64 s[42:43], 0x2000
	s_nop 0
	v_addc_co_u32_e32 v11, vcc, 0, v3, vcc
	global_load_dwordx4 v[18:21], v[10:11], off offset:-4096
	global_load_dwordx4 v[22:25], v[6:7], off offset:48
	global_load_dwordx4 v[26:29], v[6:7], off offset:32
	global_load_dwordx4 v[30:33], v[6:7], off offset:16
	ds_bpermute_b32 v8, v208, v4
	s_waitcnt vmcnt(3)
	v_mul_f32_e32 v6, v15, v19
	v_fmac_f32_e32 v6, v14, v18
	v_fmac_f32_e32 v6, v16, v20
	s_waitcnt vmcnt(0)
	v_mul_f32_e32 v7, v51, v31
	v_fmac_f32_e32 v7, v50, v30
	v_fmac_f32_e32 v6, v17, v21
	v_fmac_f32_e32 v7, v12, v32
	v_add_f32_e32 v6, 0, v6
	v_fmac_f32_e32 v7, v13, v33
	v_add_f32_e32 v6, v6, v7
	v_mul_f32_e32 v7, v39, v27
	v_fmac_f32_e32 v7, v38, v26
	v_fmac_f32_e32 v7, v40, v28
	v_fmac_f32_e32 v7, v9, v29
	v_add_f32_e32 v6, v6, v7
	v_mul_f32_e32 v7, v35, v23
	v_fmac_f32_e32 v7, v34, v22
	v_fmac_f32_e32 v7, v36, v24
	v_fmac_f32_e32 v7, v5, v25
	v_add_f32_e32 v6, v6, v7
	ds_bpermute_b32 v7, v179, v6
	s_waitcnt lgkmcnt(0)
	v_add_f32_e32 v6, v6, v7
	ds_bpermute_b32 v7, v204, v6
	s_waitcnt lgkmcnt(0)
	v_add_f32_e32 v6, v6, v7
	ds_bpermute_b32 v7, v205, v6
	s_waitcnt lgkmcnt(0)
	v_add_f32_e32 v6, v6, v7
	ds_bpermute_b32 v7, v206, v6
	s_waitcnt lgkmcnt(0)
	v_add_f32_e32 v6, v6, v7
	ds_bpermute_b32 v7, v207, v6
	s_waitcnt lgkmcnt(0)
	v_add_f32_e32 v37, v6, v7
	v_lshl_add_u64 v[6:7], v[2:3], 0, s[42:43]
	global_load_dwordx4 v[18:21], v[10:11], off
	global_load_dwordx4 v[22:25], v[6:7], off offset:48
	global_load_dwordx4 v[26:29], v[6:7], off offset:32
	global_load_dwordx4 v[30:33], v[6:7], off offset:16
	s_mov_b64 s[42:43], 0x3000
	v_lshl_add_u64 v[10:11], v[2:3], 0, s[42:43]
	s_movk_i32 s42, 0x4000
	ds_bpermute_b32 v41, v208, v37
	s_waitcnt vmcnt(3)
	v_mul_f32_e32 v6, v15, v19
	v_fmac_f32_e32 v6, v14, v18
	v_fmac_f32_e32 v6, v16, v20
	s_waitcnt vmcnt(0)
	v_mul_f32_e32 v7, v51, v31
	v_fmac_f32_e32 v7, v50, v30
	v_fmac_f32_e32 v6, v17, v21
	v_fmac_f32_e32 v7, v12, v32
	v_add_f32_e32 v6, 0, v6
	v_fmac_f32_e32 v7, v13, v33
	v_add_f32_e32 v6, v6, v7
	v_mul_f32_e32 v7, v39, v27
	v_fmac_f32_e32 v7, v38, v26
	v_fmac_f32_e32 v7, v40, v28
	v_fmac_f32_e32 v7, v9, v29
	v_add_f32_e32 v6, v6, v7
	v_mul_f32_e32 v7, v35, v23
	v_fmac_f32_e32 v7, v34, v22
	v_fmac_f32_e32 v7, v36, v24
	v_fmac_f32_e32 v7, v5, v25
	v_add_f32_e32 v6, v6, v7
	ds_bpermute_b32 v7, v179, v6
	s_waitcnt lgkmcnt(0)
; DEVI float wave_sum(float v) {
; #pragma unroll
;     for (int o = 1; o < 64; o <<= 1) v += __shfl_xor(v, o);
;     return v;
; template <int WHICH> DEVI void adaln_apply(const P& p, int l, int r, int lane_in, float (&v)[16]) {
;     ...
;         for (int jj = 0; jj < 12; ++jj) { float a = 0.f;
; #pragma unroll
;             for (int q = 0; q < 4; ++q) { const float4 w = *(const float4*)(ws + (size_t)jj * D + 4 * q); a += v[4 * q] * w.x + v[4 * q + 1] * w.y + v[4 * q + 2] * w.z + v[4 * q + 3] * w.w; }
;             dot[jj] = wave_sum(a); }
	v_add_f32_e32 v6, v6, v7
	ds_bpermute_b32 v7, v204, v6
	s_waitcnt lgkmcnt(0)
	v_add_f32_e32 v6, v6, v7
	ds_bpermute_b32 v7, v205, v6
	s_waitcnt lgkmcnt(0)
	v_add_f32_e32 v6, v6, v7
	ds_bpermute_b32 v7, v206, v6
	s_waitcnt lgkmcnt(0)
	v_add_f32_e32 v6, v6, v7
	ds_bpermute_b32 v7, v207, v6
	s_waitcnt lgkmcnt(0)
	v_add_f32_e32 v42, v6, v7
	v_add_co_u32_e32 v6, vcc, s42, v2
	s_mov_b64 s[42:43], 0x4000
	s_nop 0
	v_addc_co_u32_e32 v7, vcc, 0, v3, vcc
	global_load_dwordx4 v[18:21], v[6:7], off offset:-4096
	global_load_dwordx4 v[22:25], v[10:11], off offset:48
	global_load_dwordx4 v[26:29], v[10:11], off offset:32
	global_load_dwordx4 v[30:33], v[10:11], off offset:16
	ds_bpermute_b32 v43, v208, v42
	s_waitcnt vmcnt(3)
	v_mul_f32_e32 v10, v15, v19
	v_fmac_f32_e32 v10, v14, v18
	v_fmac_f32_e32 v10, v16, v20
	s_waitcnt vmcnt(0)
	v_mul_f32_e32 v11, v51, v31
	v_fmac_f32_e32 v11, v50, v30
	v_fmac_f32_e32 v10, v17, v21
	v_fmac_f32_e32 v11, v12, v32
	v_add_f32_e32 v10, 0, v10
	v_fmac_f32_e32 v11, v13, v33
	v_add_f32_e32 v10, v10, v11
	v_mul_f32_e32 v11, v39, v27
	v_fmac_f32_e32 v11, v38, v26
	v_fmac_f32_e32 v11, v40, v28
	v_fmac_f32_e32 v11, v9, v29
	v_add_f32_e32 v10, v10, v11
	v_mul_f32_e32 v11, v35, v23
	v_fmac_f32_e32 v11, v34, v22
	v_fmac_f32_e32 v11, v36, v24
	v_fmac_f32_e32 v11, v5, v25
	v_add_f32_e32 v10, v10, v11
	ds_bpermute_b32 v11, v179, v10
	s_waitcnt lgkmcnt(0)
	v_add_f32_e32 v10, v10, v11
	ds_bpermute_b32 v11, v204, v10
	s_waitcnt lgkmcnt(0)
	v_add_f32_e32 v10, v10, v11
	ds_bpermute_b32 v11, v205, v10
	s_waitcnt lgkmcnt(0)
	v_add_f32_e32 v10, v10, v11
	ds_bpermute_b32 v11, v206, v10
	s_waitcnt lgkmcnt(0)
	v_add_f32_e32 v10, v10, v11
	ds_bpermute_b32 v11, v207, v10
	s_waitcnt lgkmcnt(0)
	v_add_f32_e32 v44, v10, v11
	v_lshl_add_u64 v[10:11], v[2:3], 0, s[42:43]
	global_load_dwordx4 v[18:21], v[6:7], off
	global_load_dwordx4 v[22:25], v[10:11], off offset:48
	global_load_dwordx4 v[26:29], v[10:11], off offset:32
	global_load_dwordx4 v[30:33], v[10:11], off offset:16
	s_mov_b64 s[42:43], 0x5000
	v_lshl_add_u64 v[10:11], v[2:3], 0, s[42:43]
	s_movk_i32 s42, 0x6000
	ds_bpermute_b32 v45, v208, v44
	s_waitcnt vmcnt(3)
	v_mul_f32_e32 v6, v15, v19
	v_fmac_f32_e32 v6, v14, v18
	v_fmac_f32_e32 v6, v16, v20
	s_waitcnt vmcnt(0)
	v_mul_f32_e32 v7, v51, v31
	v_fmac_f32_e32 v7, v50, v30
	v_fmac_f32_e32 v6, v17, v21
	v_fmac_f32_e32 v7, v12, v32
	v_add_f32_e32 v6, 0, v6
	v_fmac_f32_e32 v7, v13, v33
	v_add_f32_e32 v6, v6, v7
	v_mul_f32_e32 v7, v39, v27
	v_fmac_f32_e32 v7, v38, v26
	v_fmac_f32_e32 v7, v40, v28
	v_fmac_f32_e32 v7, v9, v29
	v_add_f32_e32 v6, v6, v7
	v_mul_f32_e32 v7, v35, v23
	v_fmac_f32_e32 v7, v34, v22
	v_fmac_f32_e32 v7, v36, v24
	v_fmac_f32_e32 v7, v5, v25
	v_add_f32_e32 v6, v6, v7
	ds_bpermute_b32 v7, v179, v6
	s_waitcnt lgkmcnt(0)
	v_add_f32_e32 v6, v6, v7
	ds_bpermute_b32 v7, v204, v6
	s_waitcnt lgkmcnt(0)
	v_add_f32_e32 v6, v6, v7
	ds_bpermute_b32 v7, v205, v6
	s_waitcnt lgkmcnt(0)
	v_add_f32_e32 v6, v6, v7
	ds_bpermute_b32 v7, v206, v6
	s_waitcnt lgkmcnt(0)
	v_add_f32_e32 v6, v6, v7
	ds_bpermute_b32 v7, v207, v6
	s_waitcnt lgkmcnt(0)
	v_add_f32_e32 v46, v6, v7
	v_add_co_u32_e32 v6, vcc, s42, v2
	s_mov_b64 s[42:43], 0x6000
	s_nop 0
	v_addc_co_u32_e32 v7, vcc, 0, v3, vcc
	global_load_dwordx4 v[18:21], v[6:7], off offset:-4096
	global_load_dwordx4 v[22:25], v[10:11], off offset:48
	global_load_dwordx4 v[26:29], v[10:11], off offset:32
	global_load_dwordx4 v[30:33], v[10:11], off offset:16
	ds_bpermute_b32 v47, v208, v46
	s_waitcnt vmcnt(3)
	v_mul_f32_e32 v10, v15, v19
	v_fmac_f32_e32 v10, v14, v18
	v_fmac_f32_e32 v10, v16, v20
	s_waitcnt vmcnt(0)
	v_mul_f32_e32 v11, v51, v31
	v_fmac_f32_e32 v11, v50, v30
	v_fmac_f32_e32 v10, v17, v21
	v_fmac_f32_e32 v11, v12, v32
	v_add_f32_e32 v10, 0, v10
	v_fmac_f32_e32 v11, v13, v33
	v_add_f32_e32 v10, v10, v11
	v_mul_f32_e32 v11, v39, v27
	v_fmac_f32_e32 v11, v38, v26
	v_fmac_f32_e32 v11, v40, v28
	v_fmac_f32_e32 v11, v9, v29
	v_add_f32_e32 v10, v10, v11
	v_mul_f32_e32 v11, v35, v23
	v_fmac_f32_e32 v11, v34, v22
	v_fmac_f32_e32 v11, v36, v24
	v_fmac_f32_e32 v11, v5, v25
	v_add_f32_e32 v10, v10, v11
	ds_bpermute_b32 v11, v179, v10
	s_waitcnt lgkmcnt(0)
	v_add_f32_e32 v10, v10, v11
	ds_bpermute_b32 v11, v204, v10
	s_waitcnt lgkmcnt(0)
	v_add_f32_e32 v10, v10, v11
	ds_bpermute_b32 v11, v205, v10
	s_waitcnt lgkmcnt(0)
	v_add_f32_e32 v10, v10, v11
	ds_bpermute_b32 v11, v206, v10
	s_waitcnt lgkmcnt(0)
	v_add_f32_e32 v10, v10, v11
	ds_bpermute_b32 v11, v207, v10
	s_waitcnt lgkmcnt(0)
	v_add_f32_e32 v48, v10, v11
	v_lshl_add_u64 v[10:11], v[2:3], 0, s[42:43]
	global_load_dwordx4 v[18:21], v[6:7], off
	global_load_dwordx4 v[22:25], v[10:11], off offset:48
	global_load_dwordx4 v[26:29], v[10:11], off offset:32
	global_load_dwordx4 v[30:33], v[10:11], off offset:16
	s_mov_b64 s[42:43], 0x7000
	v_lshl_add_u64 v[10:11], v[2:3], 0, s[42:43]
	s_mov_b32 s42, 0x8000
	ds_bpermute_b32 v49, v208, v48
	s_waitcnt vmcnt(3)
	v_mul_f32_e32 v6, v15, v19
	v_fmac_f32_e32 v6, v14, v18
	v_fmac_f32_e32 v6, v16, v20
	s_waitcnt vmcnt(0)
	v_mul_f32_e32 v7, v51, v31
	v_fmac_f32_e32 v7, v50, v30
	v_fmac_f32_e32 v6, v17, v21
	v_fmac_f32_e32 v7, v12, v32
	v_add_f32_e32 v6, 0, v6
	v_fmac_f32_e32 v7, v13, v33
	v_add_f32_e32 v6, v6, v7
	v_mul_f32_e32 v7, v39, v27
	v_fmac_f32_e32 v7, v38, v26
	v_fmac_f32_e32 v7, v40, v28
	v_fmac_f32_e32 v7, v9, v29
	v_add_f32_e32 v6, v6, v7
	v_mul_f32_e32 v7, v35, v23
	v_fmac_f32_e32 v7, v34, v22
	v_fmac_f32_e32 v7, v36, v24
	v_fmac_f32_e32 v7, v5, v25
	v_add_f32_e32 v6, v6, v7
	ds_bpermute_b32 v7, v179, v6
	s_waitcnt lgkmcnt(0)
	v_add_f32_e32 v6, v6, v7
	ds_bpermute_b32 v7, v204, v6
	s_waitcnt lgkmcnt(0)
; DEVI float wave_sum(float v) {
; #pragma unroll
;     for (int o = 1; o < 64; o <<= 1) v += __shfl_xor(v, o);
;     return v;
; template <int WHICH> DEVI void adaln_apply(const P& p, int l, int r, int lane_in, float (&v)[16]) {
;     ...
;         for (int jj = 0; jj < 12; ++jj) { float a = 0.f;
; #pragma unroll
;             for (int q = 0; q < 4; ++q) { const float4 w = *(const float4*)(ws + (size_t)jj * D + 4 * q); a += v[4 * q] * w.x + v[4 * q + 1] * w.y + v[4 * q + 2] * w.z + v[4 * q + 3] * w.w; }
;             dot[jj] = wave_sum(a); }
	v_add_f32_e32 v6, v6, v7
	ds_bpermute_b32 v7, v205, v6
	s_waitcnt lgkmcnt(0)
	v_add_f32_e32 v6, v6, v7
	ds_bpermute_b32 v7, v206, v6
	s_waitcnt lgkmcnt(0)
	v_add_f32_e32 v6, v6, v7
	ds_bpermute_b32 v7, v207, v6
	s_waitcnt lgkmcnt(0)
	v_add_f32_e32 v52, v6, v7
	v_add_co_u32_e32 v6, vcc, s42, v2
	s_mov_b64 s[42:43], 0x9000
	s_nop 0
	v_addc_co_u32_e32 v7, vcc, 0, v3, vcc
	global_load_dwordx4 v[18:21], v[6:7], off offset:-4096
	global_load_dwordx4 v[22:25], v[10:11], off offset:48
	global_load_dwordx4 v[26:29], v[10:11], off offset:32
	global_load_dwordx4 v[30:33], v[10:11], off offset:16
	ds_bpermute_b32 v53, v208, v52
	s_waitcnt vmcnt(3)
	v_mul_f32_e32 v10, v15, v19
	v_fmac_f32_e32 v10, v14, v18
	v_fmac_f32_e32 v10, v16, v20
	s_waitcnt vmcnt(0)
	v_mul_f32_e32 v11, v51, v31
	v_fmac_f32_e32 v11, v50, v30
	v_fmac_f32_e32 v10, v17, v21
	v_fmac_f32_e32 v11, v12, v32
	v_add_f32_e32 v10, 0, v10
	v_fmac_f32_e32 v11, v13, v33
	v_add_f32_e32 v10, v10, v11
	v_mul_f32_e32 v11, v39, v27
	v_fmac_f32_e32 v11, v38, v26
	v_fmac_f32_e32 v11, v40, v28
	v_fmac_f32_e32 v11, v9, v29
	v_add_f32_e32 v10, v10, v11
	v_mul_f32_e32 v11, v35, v23
	v_fmac_f32_e32 v11, v34, v22
	v_fmac_f32_e32 v11, v36, v24
	v_fmac_f32_e32 v11, v5, v25
	v_add_f32_e32 v10, v10, v11
	ds_bpermute_b32 v11, v179, v10
	s_waitcnt lgkmcnt(0)
	v_add_f32_e32 v10, v10, v11
	ds_bpermute_b32 v11, v204, v10
	s_waitcnt lgkmcnt(0)
	v_add_f32_e32 v10, v10, v11
	ds_bpermute_b32 v11, v205, v10
	s_waitcnt lgkmcnt(0)
	v_add_f32_e32 v10, v10, v11
	ds_bpermute_b32 v11, v206, v10
	s_waitcnt lgkmcnt(0)
	v_add_f32_e32 v10, v10, v11
	ds_bpermute_b32 v11, v207, v10
	s_waitcnt lgkmcnt(0)
	v_add_f32_e32 v54, v10, v11
	v_lshl_add_u64 v[10:11], v[2:3], 0, s[38:39]
	global_load_dwordx4 v[18:21], v[6:7], off
	global_load_dwordx4 v[22:25], v[10:11], off offset:48
	global_load_dwordx4 v[26:29], v[10:11], off offset:32
	global_load_dwordx4 v[30:33], v[10:11], off offset:16
	ds_bpermute_b32 v55, v208, v54
	s_waitcnt vmcnt(3)
	v_mul_f32_e32 v6, v15, v19
	v_fmac_f32_e32 v6, v14, v18
	v_fmac_f32_e32 v6, v16, v20
	s_waitcnt vmcnt(0)
	v_mul_f32_e32 v7, v51, v31
	v_fmac_f32_e32 v7, v50, v30
	v_fmac_f32_e32 v6, v17, v21
	v_fmac_f32_e32 v7, v12, v32
	v_add_f32_e32 v6, 0, v6
	v_fmac_f32_e32 v7, v13, v33
	v_add_f32_e32 v6, v6, v7
	v_mul_f32_e32 v7, v39, v27
	v_fmac_f32_e32 v7, v38, v26
	v_fmac_f32_e32 v7, v40, v28
	v_fmac_f32_e32 v7, v9, v29
	v_add_f32_e32 v6, v6, v7
	v_mul_f32_e32 v7, v35, v23
	v_fmac_f32_e32 v7, v34, v22
	v_fmac_f32_e32 v7, v36, v24
	v_fmac_f32_e32 v7, v5, v25
	v_add_f32_e32 v6, v6, v7
	ds_bpermute_b32 v7, v179, v6
	s_waitcnt lgkmcnt(0)
	v_add_f32_e32 v6, v6, v7
	ds_bpermute_b32 v7, v204, v6
	s_waitcnt lgkmcnt(0)
	v_add_f32_e32 v6, v6, v7
	ds_bpermute_b32 v7, v205, v6
	s_waitcnt lgkmcnt(0)
	v_add_f32_e32 v6, v6, v7
	ds_bpermute_b32 v7, v206, v6
	s_waitcnt lgkmcnt(0)
	v_add_f32_e32 v6, v6, v7
	ds_bpermute_b32 v7, v207, v6
	s_waitcnt lgkmcnt(0)
	v_add_f32_e32 v56, v6, v7
	v_lshl_add_u64 v[6:7], v[2:3], 0, s[42:43]
	s_mov_b32 s42, 0xa000
	v_add_co_u32_e32 v10, vcc, s42, v2
	s_mov_b64 s[42:43], 0xa000
	s_nop 0
	v_addc_co_u32_e32 v11, vcc, 0, v3, vcc
	global_load_dwordx4 v[18:21], v[10:11], off offset:-4096
	global_load_dwordx4 v[22:25], v[6:7], off offset:48
	global_load_dwordx4 v[26:29], v[6:7], off offset:32
	global_load_dwordx4 v[30:33], v[6:7], off offset:16
	ds_bpermute_b32 v57, v208, v56
	s_waitcnt vmcnt(3)
	v_mul_f32_e32 v6, v15, v19
	v_fmac_f32_e32 v6, v14, v18
	v_fmac_f32_e32 v6, v16, v20
	s_waitcnt vmcnt(0)
	v_mul_f32_e32 v7, v51, v31
	v_fmac_f32_e32 v7, v50, v30
	v_fmac_f32_e32 v6, v17, v21
	v_fmac_f32_e32 v7, v12, v32
	v_add_f32_e32 v6, 0, v6
	v_fmac_f32_e32 v7, v13, v33
	v_add_f32_e32 v6, v6, v7
	v_mul_f32_e32 v7, v39, v27
	v_fmac_f32_e32 v7, v38, v26
	v_fmac_f32_e32 v7, v40, v28
	v_fmac_f32_e32 v7, v9, v29
	v_add_f32_e32 v6, v6, v7
	v_mul_f32_e32 v7, v35, v23
	v_fmac_f32_e32 v7, v34, v22
	v_fmac_f32_e32 v7, v36, v24
	v_lshl_add_u64 v[30:31], v[2:3], 0, s[42:43]
	v_fmac_f32_e32 v7, v5, v25
	global_load_dwordx4 v[18:21], v[10:11], off
	global_load_dwordx4 v[22:25], v[30:31], off offset:48
	global_load_dwordx4 v[26:29], v[30:31], off offset:32
	s_nop 0
	global_load_dwordx4 v[30:33], v[30:31], off offset:16
	s_mov_b64 s[42:43], 0xb000
	v_add_f32_e32 v6, v6, v7
	ds_bpermute_b32 v7, v179, v6
	s_waitcnt lgkmcnt(0)
	v_add_f32_e32 v6, v6, v7
	ds_bpermute_b32 v7, v204, v6
	s_waitcnt lgkmcnt(0)
	v_add_f32_e32 v6, v6, v7
	ds_bpermute_b32 v7, v205, v6
	s_waitcnt lgkmcnt(0)
	v_add_f32_e32 v6, v6, v7
	ds_bpermute_b32 v7, v206, v6
	s_waitcnt lgkmcnt(0)
	v_add_f32_e32 v6, v6, v7
	ds_bpermute_b32 v7, v207, v6
	s_waitcnt lgkmcnt(0)
	v_add_f32_e32 v6, v6, v7
	ds_bpermute_b32 v7, v208, v6
	s_waitcnt vmcnt(3)
	v_mul_f32_e32 v10, v15, v19
	v_fmac_f32_e32 v10, v14, v18
	v_fmac_f32_e32 v10, v16, v20
	s_waitcnt vmcnt(0)
	v_mul_f32_e32 v11, v51, v31
	v_fmac_f32_e32 v11, v50, v30
	v_fmac_f32_e32 v10, v17, v21
	v_fmac_f32_e32 v11, v12, v32
	v_add_f32_e32 v10, 0, v10
	v_fmac_f32_e32 v11, v13, v33
	v_add_f32_e32 v10, v10, v11
	v_mul_f32_e32 v11, v39, v27
	v_fmac_f32_e32 v11, v38, v26
	v_fmac_f32_e32 v11, v40, v28
	v_fmac_f32_e32 v11, v9, v29
	v_add_f32_e32 v10, v10, v11
	v_mul_f32_e32 v11, v35, v23
	v_lshl_add_u64 v[30:31], v[2:3], 0, s[42:43]
	s_mov_b32 s42, 0xb000
	v_fmac_f32_e32 v11, v34, v22
	v_add_co_u32_e32 v2, vcc, s42, v2
	v_fmac_f32_e32 v11, v36, v24
	s_nop 0
	v_addc_co_u32_e32 v3, vcc, 0, v3, vcc
	v_fmac_f32_e32 v11, v5, v25
	global_load_dwordx4 v[26:29], v[2:3], off
	global_load_dwordx4 v[18:21], v[30:31], off offset:48
	global_load_dwordx4 v[22:25], v[30:31], off offset:32
	s_nop 0
	global_load_dwordx4 v[30:33], v[30:31], off offset:16
	v_add_f32_e32 v10, v10, v11
	ds_bpermute_b32 v11, v179, v10
	v_cmp_lt_i32_e32 vcc, 7, v58
	s_waitcnt lgkmcnt(0)
;     DEVI float* dt() const { return (float*)(ws + WS_DT); }
;     DEVI float* logf() const { return (float*)(ws + WS_LOGF); }
; DEVI float softplus_f(float x) { return x > 20.f ? x : log1pf(expf(x)); }
; template <int WHICH> DEVI void adaln_apply(const P& p, int l, int r, int lane_in, float (&v)[16]) {
;     ...
;             dot[jj] = wave_sum(a); }
;         if (lane < 8) {
;             float d = dot[0];
; #pragma unroll
;             for (int jj = 1; jj < 8; ++jj) d = (lane == jj) ? dot[jj] : d;
;             p.dt()[(size_t)r * 8 + lane] = softplus_f(d + dtb[lane]);
;         } else if (lane < 12) {
;             const int hd = lane - 8; float d = dot[8];
; #pragma unroll
;             for (int jj = 9; jj < 12; ++jj) d = (lane == jj) ? dot[jj] : d;
;             const float lf = -softplus_f(-(d + fb[hd]));
;             p.logf()[(size_t)r * 4 + hd] = lf;
;             if (r < M_P) p.out[OUT_LFP + ((size_t)l * M_P + r) * 4 + hd] = lf; else p.out[OUT_LFS + ((size_t)l * M_S + (r - M_P)) * 4 + hd] = lf;
;         }
	v_add_f32_e32 v10, v10, v11
	ds_bpermute_b32 v11, v204, v10
	s_waitcnt lgkmcnt(0)
	v_add_f32_e32 v10, v10, v11
	ds_bpermute_b32 v11, v205, v10
	s_waitcnt lgkmcnt(0)
	v_add_f32_e32 v10, v10, v11
	ds_bpermute_b32 v11, v206, v10
	s_waitcnt lgkmcnt(0)
	v_add_f32_e32 v10, v10, v11
	ds_bpermute_b32 v11, v207, v10
	s_waitcnt lgkmcnt(0)
	v_add_f32_e32 v10, v10, v11
	ds_bpermute_b32 v11, v208, v10
	s_waitcnt vmcnt(3)
	v_mul_f32_e32 v2, v15, v27
	v_fmac_f32_e32 v2, v14, v26
	v_fmac_f32_e32 v2, v16, v28
	s_waitcnt vmcnt(0)
	v_mul_f32_e32 v3, v51, v31
	v_fmac_f32_e32 v3, v50, v30
	v_fmac_f32_e32 v2, v17, v29
	v_fmac_f32_e32 v3, v12, v32
	v_add_f32_e32 v2, 0, v2
	v_fmac_f32_e32 v3, v13, v33
	v_add_f32_e32 v2, v2, v3
	v_mul_f32_e32 v3, v39, v23
	v_fmac_f32_e32 v3, v38, v22
	v_fmac_f32_e32 v3, v40, v24
	v_fmac_f32_e32 v3, v9, v25
	v_add_f32_e32 v2, v2, v3
	v_mul_f32_e32 v3, v35, v19
	v_fmac_f32_e32 v3, v34, v18
	v_fmac_f32_e32 v3, v36, v20
	v_fmac_f32_e32 v3, v5, v21
	v_add_f32_e32 v2, v2, v3
	ds_bpermute_b32 v3, v179, v2
	s_waitcnt lgkmcnt(0)
	v_add_f32_e32 v2, v2, v3
	ds_bpermute_b32 v3, v204, v2
	s_waitcnt lgkmcnt(0)
	v_add_f32_e32 v2, v2, v3
	ds_bpermute_b32 v3, v205, v2
	s_waitcnt lgkmcnt(0)
	v_add_f32_e32 v2, v2, v3
	ds_bpermute_b32 v3, v206, v2
	s_waitcnt lgkmcnt(0)
	v_add_f32_e32 v2, v2, v3
	ds_bpermute_b32 v3, v207, v2
	s_waitcnt lgkmcnt(0)
	v_add_f32_e32 v2, v2, v3
	ds_bpermute_b32 v3, v208, v2
	s_and_saveexec_b64 s[42:43], vcc
	s_xor_b64 s[42:43], exec, s[42:43]
	s_cbranch_execz .LBB0_1121
	v_cmp_gt_u32_e32 vcc, 12, v58
	s_and_saveexec_b64 s[44:45], vcc
	s_cbranch_execz .LBB0_1120
	s_add_u32 s40, s40, s24
	s_addc_u32 s41, s41, s25
	v_add_u32_e32 v66, -8, v58
	v_lshl_add_u64 v[4:5], v[66:67], 2, s[40:41]
	global_load_dword v4, v[4:5], off
	v_add_f32_e32 v5, v56, v57
	v_add_f32_e32 v6, v6, v7
	v_cmp_eq_u32_e32 vcc, 9, v58
	v_add_f32_e32 v7, v10, v11
	s_waitcnt lgkmcnt(0)
	v_add_f32_e32 v2, v2, v3
	v_cndmask_b32_e32 v3, v5, v6, vcc
	v_cmp_eq_u32_e32 vcc, 10, v58
	s_mov_b32 s40, 0xc1a00000
	s_nop 0
	v_cndmask_b32_e32 v3, v3, v7, vcc
	v_cmp_eq_u32_e32 vcc, 11, v58
	s_nop 1
	v_cndmask_b32_e32 v2, v3, v2, vcc
	s_waitcnt vmcnt(0)
	v_add_f32_e32 v2, v2, v4
	v_xor_b32_e32 v3, 0x80000000, v2
	v_cmp_ngt_f32_e32 vcc, s40, v2
	s_and_saveexec_b64 s[40:41], vcc
	s_cbranch_execz .LBB0_1119
	v_mul_f32_e32 v3, 0xbfb8aa3b, v2
	v_rndne_f32_e32 v4, v3
	s_mov_b32 s66, 0xbfb8aa3b
	v_sub_f32_e32 v5, v3, v4
	v_fma_f32 v3, v2, s66, -v3
	v_fmac_f32_e32 v3, 0xb2a5705f, v2
	v_add_f32_e32 v3, v5, v3
	v_cvt_i32_f32_e32 v4, v4
	v_exp_f32_e32 v3, v3
	s_mov_b32 s66, 0x42ce8ed0
	v_cmp_nlt_f32_e32 vcc, s66, v2
	s_mov_b32 s66, 0xc2b17218
	v_ldexp_f32 v3, v3, v4
	v_cndmask_b32_e32 v3, 0, v3, vcc
	v_cmp_ngt_f32_e32 vcc, s66, v2
	s_mov_b32 s66, 0x3f2aaaab
	s_nop 0
	v_cndmask_b32_e32 v16, v215, v3, vcc
	v_add_f32_e32 v4, 1.0, v16
	v_add_f32_e32 v2, -1.0, v4
	v_sub_f32_e32 v3, v2, v4
	v_add_f32_e32 v3, 1.0, v3
	v_sub_f32_e32 v2, v16, v2
	v_add_f32_e32 v5, v2, v3
	v_frexp_mant_f32_e32 v6, v4
	v_cvt_f64_f32_e32 v[2:3], v4
	v_frexp_exp_i32_f64_e32 v2, v[2:3]
	v_cmp_gt_f32_e32 vcc, s66, v6
	s_mov_b32 s66, 0x3f317218
	s_nop 0
	v_subbrev_co_u32_e32 v10, vcc, 0, v2, vcc
	v_sub_u32_e32 v2, 0, v10
	v_ldexp_f32 v3, v4, v2
	v_add_f32_e32 v4, -1.0, v3
	v_add_f32_e32 v6, 1.0, v3
	v_ldexp_f32 v2, v5, v2
	v_add_f32_e32 v5, 1.0, v4
	v_add_f32_e32 v7, -1.0, v6
	v_sub_f32_e32 v5, v3, v5
	v_sub_f32_e32 v3, v3, v7
	v_add_f32_e32 v5, v2, v5
	v_add_f32_e32 v2, v2, v3
	v_add_f32_e32 v11, v6, v2
	v_rcp_f32_e32 v13, v11
	v_sub_f32_e32 v3, v6, v11
	v_add_f32_e32 v12, v2, v3
	v_add_f32_e32 v3, v4, v5
	v_mul_f32_e32 v15, v3, v13
	v_sub_f32_e32 v2, v4, v3
	v_mul_f32_e32 v4, v11, v15
	v_fma_f32 v6, v15, v11, -v4
	v_fmac_f32_e32 v6, v15, v12
	v_add_f32_e32 v14, v5, v2
	v_add_f32_e32 v2, v4, v6
	v_sub_f32_e32 v5, v3, v2
	v_pk_add_f32 v[8:9], v[2:3], v[4:5] neg_lo:[0,1] neg_hi:[0,1]
	v_mov_b32_e32 v7, v2
	v_pk_add_f32 v[2:3], v[8:9], v[6:7] neg_lo:[0,1] neg_hi:[0,1]
	s_nop 0
	v_add_f32_e32 v3, v14, v3
	v_add_f32_e32 v2, v2, v3
	v_add_f32_e32 v3, v5, v2
	v_mul_f32_e32 v14, v13, v3
	v_mul_f32_e32 v4, v11, v14
	v_fma_f32 v6, v14, v11, -v4
	v_fmac_f32_e32 v6, v14, v12
	v_sub_f32_e32 v5, v5, v3
	v_add_f32_e32 v11, v2, v5
	v_add_f32_e32 v2, v4, v6
	v_sub_f32_e32 v5, v3, v2
	v_pk_add_f32 v[8:9], v[2:3], v[4:5] neg_lo:[0,1] neg_hi:[0,1]
	v_mov_b32_e32 v7, v2
	v_pk_add_f32 v[2:3], v[8:9], v[6:7] neg_lo:[0,1] neg_hi:[0,1]
	s_nop 0
	v_add_f32_e32 v3, v11, v3
	v_add_f32_e32 v2, v2, v3
	v_add_f32_e32 v3, v15, v14
	v_add_f32_e32 v2, v5, v2
	v_sub_f32_e32 v4, v3, v15
	v_mul_f32_e32 v2, v13, v2
	v_sub_f32_e32 v4, v14, v4
	v_add_f32_e32 v4, v4, v2
	v_add_f32_e32 v6, v3, v4
	v_mul_f32_e32 v7, v6, v6
	v_fmamk_f32 v2, v7, 0x3e9b6dac, v212
	v_fmaak_f32 v177, v7, v2, 0x3f2aaada
	v_cvt_f32_i32_e32 v2, v10
	v_sub_f32_e32 v3, v6, v3
	v_sub_f32_e32 v3, v4, v3
	v_ldexp_f32 v8, v3, 1
	v_mul_f32_e32 v3, v6, v7
	v_ldexp_f32 v5, v6, 1
	v_pk_mul_f32 v[6:7], v[2:3], v[176:177]
	s_nop 0
	v_fma_f32 v4, v2, s66, -v6
	v_fmac_f32_e32 v4, 0xb102e308, v2
	v_pk_add_f32 v[2:3], v[6:7], v[4:5]
	s_mov_b32 s66, 0x7f800000
	v_sub_f32_e32 v5, v3, v5
	v_sub_f32_e32 v5, v7, v5
	v_add_f32_e32 v9, v8, v5
	v_mov_b32_e32 v8, v6
	v_pk_add_f32 v[6:7], v[2:3], v[6:7] neg_lo:[0,1] neg_hi:[0,1]
	v_pk_add_f32 v[10:11], v[2:3], v[8:9]
	v_mov_b32_e32 v5, v2
	v_mov_b32_e32 v7, v11
	v_pk_add_f32 v[12:13], v[4:5], v[6:7] neg_lo:[0,1] neg_hi:[0,1]
	v_pk_add_f32 v[4:5], v[4:5], v[6:7]
	v_mov_b32_e32 v8, v9
	v_pk_add_f32 v[6:7], v[4:5], v[2:3] op_sel:[1,0] op_sel_hi:[0,1] neg_lo:[0,1] neg_hi:[0,1]
	v_pk_add_f32 v[14:15], v[10:11], v[6:7] op_sel_hi:[1,0] neg_lo:[0,1] neg_hi:[0,1]
	v_mov_b32_e32 v10, v11
	v_mov_b32_e32 v11, v5
	v_pk_mov_b32 v[6:7], v[2:3], v[6:7] op_sel:[1,0]
	v_mov_b32_e32 v9, v2
	v_pk_add_f32 v[6:7], v[10:11], v[6:7] neg_lo:[0,1] neg_hi:[0,1]
	v_mov_b32_e32 v14, v12
	v_pk_add_f32 v[2:3], v[8:9], v[6:7] neg_lo:[0,1] neg_hi:[0,1]
	v_mov_b32_e32 v13, v5
	v_pk_add_f32 v[6:7], v[14:15], v[2:3]
	v_cmp_neq_f32_e32 vcc, s66, v16
	v_pk_add_f32 v[8:9], v[6:7], v[6:7] op_sel:[0,1] op_sel_hi:[1,0]
	s_mov_b32 s66, 0x33800000
	v_pk_add_f32 v[4:5], v[4:5], v[8:9] op_sel:[1,0] op_sel_hi:[0,1]
	v_mov_b32_e32 v7, v4
	v_pk_add_f32 v[10:11], v[6:7], v[12:13] neg_lo:[0,1] neg_hi:[0,1]
	v_mov_b32_e32 v3, v8
	v_sub_f32_e32 v5, v6, v10
	v_pk_add_f32 v[2:3], v[2:3], v[10:11] neg_lo:[0,1] neg_hi:[0,1]
	v_sub_f32_e32 v5, v12, v5
	v_add_f32_e32 v2, v2, v5
	v_add_f32_e32 v2, v2, v3
	v_add_f32_e32 v2, v4, v2
	v_cndmask_b32_e32 v2, v215, v2, vcc
	v_cmp_lt_f32_e64 vcc, |v16|, s66
	s_nop 1
	v_cndmask_b32_e32 v3, v2, v16, vcc
